# back-edge rotation (guide 7.11) on the six GEMM K-loops: next iteration's pointer/counter SALU moved before the loop-back barrier
# baseline (speedup 1.0000x reference)
; #define PG8_STAGE(bufoff, gbase, voff) do { _Pragma("unroll") for (int _i = 0; _i < 2; ++_i) \
;         __builtin_amdgcn_global_load_lds((const unsigned*)((const char*)(gbase) + (voff)[_i]), (PG8_LAS unsigned*)(lds + (bufoff) + ldsw + _i * 8192), 16, 0, 0); } while (0)
; #define PG8_LDA(dst, b, h) do { _Pragma("unroll") for (int m = 0; m < 4; ++m) _Pragma("unroll") for (int k = 0; k < 2; ++k) dst[m][k] = *(const PG8_LAS bf16x8*)(lds + PG8_SA(b, h) + aoff + m * 2048 + k * 1024); } while (0)
; #define PG8_LDB(dst, b, h) do { _Pragma("unroll") for (int n = 0; n < 2; ++n) _Pragma("unroll") for (int k = 0; k < 2; ++k) dst[n][k] = *(const PG8_LAS bf16x8*)(lds + PG8_SB(b, h) + boff + n * 2048 + k * 1024); } while (0)
; #define PG8_MMA(ai, bj, At, Bt) do { __builtin_amdgcn_s_setprio(1); _Pragma("unroll") for (int m = 0; m < 4; ++m) _Pragma("unroll") for (int n = 0; n < 2; ++n) _Pragma("unroll") for (int k = 0; k < 2; ++k) \
;         acc[ai][bj][m][n] = __builtin_amdgcn_mfma_f32_16x16x32_bf16(Bt[n][k], At[m][k], acc[ai][bj][m][n], 0, 0, 0); __builtin_amdgcn_s_setprio(0); } while (0)
; #define PG8_WAIT_V(n) asm volatile("s_waitcnt vmcnt(" #n ")" ::: "memory")
; #define PG8_WAIT_L(n) asm volatile("s_waitcnt lgkmcnt(" #n ")" ::: "memory")
; template <class Epi, class Sched, bool ALIGN_EPI = false, bool SP2 = false>
; __device__ __forceinline__ void gemm_phase(PG8_LAS unsigned char* lds, const Gemm g, const Sched& S, const Epi& E) {
;     ...
;             const bool last = (t == nt - 2);
;             const char* a1 = cA + (size_t)(t + 1) * kstep;
;             const char* a2 = last ? nA : cA + (size_t)(t + 2) * kstep; const char* b2 = last ? nB : cB + (size_t)(t + 2) * kstep;
;             const char* a3 = a2 + kstep; const char* b3 = b2 + kstep;
;             if (last && has_next) S.a_ready(nxt);
;             if constexpr (SP2) {
;             PG8_LDB(B0, 0, 0); PG8_LDB(B1, 0, 1); PG8_SCHED; PG8_LDA(At, 0, 0); PG8_STAGE(PG8_SA(1, 1), a1 + hstep, voffA);
;             PG8_WAIT_V(8); PG8_WAIT_L(0); PG8_BAR; PG8_MMA(0, 0, At, B0); PG8_MMA(0, 1, At, B1); PG8_BAR; PG8_SCHED;
;             PG8_LDA(At, 0, 1); PG8_STAGE(PG8_SB(0, 0), b2, voffB); PG8_STAGE(PG8_SB(0, 1), b2 + hstep, voffB); PG8_STAGE(PG8_SA(0, 0), a2, voffA);
;             PG8_WAIT_V(8); PG8_WAIT_L(0); PG8_BAR; PG8_MMA(1, 0, At, B0); PG8_MMA(1, 1, At, B1); PG8_BAR; PG8_SCHED;
.LBB0_111:
	s_add_u32 s76, s12, 0xfffc0080
	s_addc_u32 s77, s13, -1
	s_add_i32 s80, 0, 0x10000
	s_cmp_eq_u32 s69, 12
	s_cselect_b32 s79, s11, s77
	s_cselect_b32 s78, s22, s76
	s_cselect_b32 s77, s23, s67
	s_cselect_b32 s76, s40, s41
	s_add_i32 s86, 0, 0x14000
	v_add_u32_e32 v146, s80, v159
	v_add_u32_e32 v182, s86, v159
	s_branch .Lk_p1_body
.Lk_p1_head:
	s_barrier
.Lk_p1_body:
	ds_read_b128 v[134:137], v146
	ds_read_b128 v[138:141], v146 offset:1024
	ds_read_b128 v[142:145], v146 offset:2048
	ds_read_b128 v[146:149], v146 offset:3072
	ds_read_b128 v[166:169], v182
	ds_read_b128 v[170:173], v182 offset:1024
	ds_read_b128 v[174:177], v182 offset:2048
	ds_read_b128 v[182:185], v182 offset:3072
	v_lshl_add_u64 v[186:187], s[12:13], 0, v[164:165]
	s_add_i32 m0, s37, 0xc000
	ds_read_b128 v[200:203], v180
	ds_read_b128 v[204:207], v180 offset:1024
	ds_read_b128 v[208:211], v180 offset:2048
	ds_read_b128 v[212:215], v180 offset:3072
	ds_read_b128 v[216:219], v180 offset:4096
	ds_read_b128 v[220:223], v180 offset:5120
	ds_read_b128 v[224:227], v180 offset:6144
	ds_read_b128 v[228:231], v180 offset:7168
	global_load_lds_dwordx4 v[186:187], off
	v_lshl_add_u64 v[186:187], s[12:13], 0, v[162:163]
	s_add_i32 m0, s37, 0xe000
	s_nop 0
	global_load_lds_dwordx4 v[186:187], off
	s_waitcnt vmcnt(8)
	s_waitcnt lgkmcnt(0)
	s_barrier
	s_setprio 1
	s_waitcnt lgkmcnt(0)
	v_mfma_f32_16x16x32_bf16 v[130:133], v[134:137], v[200:203], v[130:133]
	v_mfma_f32_16x16x32_bf16 v[126:129], v[142:145], v[200:203], v[126:129]
	v_mfma_f32_16x16x32_bf16 v[114:117], v[134:137], v[208:211], v[114:117]
	v_mfma_f32_16x16x32_bf16 v[110:113], v[142:145], v[208:211], v[110:113]
	v_mfma_f32_16x16x32_bf16 v[98:101], v[134:137], v[216:219], v[98:101]
	v_mfma_f32_16x16x32_bf16 v[94:97], v[142:145], v[216:219], v[94:97]
	v_mfma_f32_16x16x32_bf16 v[78:81], v[134:137], v[224:227], v[78:81]
	v_mfma_f32_16x16x32_bf16 v[74:77], v[142:145], v[224:227], v[74:77]
	v_mfma_f32_16x16x32_bf16 v[130:133], v[138:141], v[204:207], v[130:133]
	v_mfma_f32_16x16x32_bf16 v[126:129], v[146:149], v[204:207], v[126:129]
	v_mfma_f32_16x16x32_bf16 v[114:117], v[138:141], v[212:215], v[114:117]
	v_mfma_f32_16x16x32_bf16 v[110:113], v[146:149], v[212:215], v[110:113]
	v_mfma_f32_16x16x32_bf16 v[98:101], v[138:141], v[220:223], v[98:101]
	v_mfma_f32_16x16x32_bf16 v[94:97], v[146:149], v[220:223], v[94:97]
	v_mfma_f32_16x16x32_bf16 v[78:81], v[138:141], v[228:231], v[78:81]
	v_mfma_f32_16x16x32_bf16 v[74:77], v[146:149], v[228:231], v[74:77]
	s_setprio 0
	s_setprio 1
	v_mfma_f32_16x16x32_bf16 v[122:125], v[166:169], v[200:203], v[122:125]
	v_mfma_f32_16x16x32_bf16 v[118:121], v[174:177], v[200:203], v[118:121]
	v_mfma_f32_16x16x32_bf16 v[106:109], v[166:169], v[208:211], v[106:109]
	v_mfma_f32_16x16x32_bf16 v[102:105], v[174:177], v[208:211], v[102:105]
	v_mfma_f32_16x16x32_bf16 v[90:93], v[166:169], v[216:219], v[90:93]
	v_mfma_f32_16x16x32_bf16 v[86:89], v[174:177], v[216:219], v[86:89]
	v_mfma_f32_16x16x32_bf16 v[70:73], v[166:169], v[224:227], v[70:73]
	v_mfma_f32_16x16x32_bf16 v[66:69], v[174:177], v[224:227], v[66:69]
	v_mfma_f32_16x16x32_bf16 v[122:125], v[170:173], v[204:207], v[122:125]
	v_mfma_f32_16x16x32_bf16 v[118:121], v[182:185], v[204:207], v[118:121]
	v_mfma_f32_16x16x32_bf16 v[106:109], v[170:173], v[212:215], v[106:109]
	v_mfma_f32_16x16x32_bf16 v[102:105], v[182:185], v[212:215], v[102:105]
	v_mfma_f32_16x16x32_bf16 v[90:93], v[170:173], v[220:223], v[90:93]
	v_mfma_f32_16x16x32_bf16 v[86:89], v[182:185], v[220:223], v[86:89]
	v_mfma_f32_16x16x32_bf16 v[70:73], v[170:173], v[228:231], v[70:73]
	v_mfma_f32_16x16x32_bf16 v[66:69], v[182:185], v[228:231], v[66:69]
	s_setprio 0
	s_barrier
	s_add_i32 s80, s80, s36
	v_lshl_add_u64 v[186:187], s[76:77], 0, v[152:153]
	s_mov_b32 m0, s80
	ds_read_b128 v[200:203], v180 offset:16384
	ds_read_b128 v[204:207], v180 offset:17408
	ds_read_b128 v[208:211], v180 offset:18432
	ds_read_b128 v[212:215], v180 offset:19456
	ds_read_b128 v[216:219], v180 offset:20480
	ds_read_b128 v[220:223], v180 offset:21504
	ds_read_b128 v[224:227], v180 offset:22528
	ds_read_b128 v[228:231], v180 offset:23552
	global_load_lds_dwordx4 v[186:187], off
	s_add_i32 m0, s80, 0x2000
	s_add_u32 s80, s76, 0x40000
	v_lshl_add_u64 v[232:233], s[76:77], 0, v[156:157]
	s_addc_u32 s81, s77, 0
	s_add_i32 s86, s86, s36
	global_load_lds_dwordx4 v[232:233], off
	v_lshl_add_u64 v[234:235], s[80:81], 0, v[152:153]
	s_mov_b32 m0, s86
	v_lshl_add_u64 v[236:237], s[78:79], 0, v[154:155]
	global_load_lds_dwordx4 v[234:235], off
	v_lshl_add_u64 v[234:235], s[80:81], 0, v[156:157]
	s_add_i32 m0, s86, 0x2000
	s_nop 0
	global_load_lds_dwordx4 v[234:235], off
	v_lshl_add_u64 v[234:235], s[78:79], 0, v[150:151]
	s_mov_b32 m0, s37
	s_nop 0
	global_load_lds_dwordx4 v[234:235], off
	s_mov_b32 m0, s42
	s_nop 0
	global_load_lds_dwordx4 v[236:237], off
	s_waitcnt vmcnt(8)
	s_waitcnt lgkmcnt(0)
	s_barrier
; #define PG8_STAGE(bufoff, gbase, voff) do { _Pragma("unroll") for (int _i = 0; _i < 2; ++_i) \
;         __builtin_amdgcn_global_load_lds((const unsigned*)((const char*)(gbase) + (voff)[_i]), (PG8_LAS unsigned*)(lds + (bufoff) + ldsw + _i * 8192), 16, 0, 0); } while (0)
; #define PG8_LDA(dst, b, h) do { _Pragma("unroll") for (int m = 0; m < 4; ++m) _Pragma("unroll") for (int k = 0; k < 2; ++k) dst[m][k] = *(const PG8_LAS bf16x8*)(lds + PG8_SA(b, h) + aoff + m * 2048 + k * 1024); } while (0)
; #define PG8_LDB(dst, b, h) do { _Pragma("unroll") for (int n = 0; n < 2; ++n) _Pragma("unroll") for (int k = 0; k < 2; ++k) dst[n][k] = *(const PG8_LAS bf16x8*)(lds + PG8_SB(b, h) + boff + n * 2048 + k * 1024); } while (0)
; #define PG8_MMA(ai, bj, At, Bt) do { __builtin_amdgcn_s_setprio(1); _Pragma("unroll") for (int m = 0; m < 4; ++m) _Pragma("unroll") for (int n = 0; n < 2; ++n) _Pragma("unroll") for (int k = 0; k < 2; ++k) \
;         acc[ai][bj][m][n] = __builtin_amdgcn_mfma_f32_16x16x32_bf16(Bt[n][k], At[m][k], acc[ai][bj][m][n], 0, 0, 0); __builtin_amdgcn_s_setprio(0); } while (0)
; #define PG8_WAIT_V(n) asm volatile("s_waitcnt vmcnt(" #n ")" ::: "memory")
; #define PG8_WAIT_L(n) asm volatile("s_waitcnt lgkmcnt(" #n ")" ::: "memory")
; #define PG8_BAR __builtin_amdgcn_s_barrier()
; #define PG8_SCHED __builtin_amdgcn_sched_barrier(0)
; template <class Epi, class Sched, bool ALIGN_EPI = false, bool SP2 = false>
; __device__ __forceinline__ void gemm_phase(PG8_LAS unsigned char* lds, const Gemm g, const Sched& S, const Epi& E) {
;     ...
;             PG8_WAIT_V(8); PG8_WAIT_L(0); PG8_BAR; PG8_MMA(1, 0, At, B0); PG8_MMA(1, 1, At, B1); PG8_BAR; PG8_SCHED;
;             PG8_LDB(B0, 1, 0); PG8_LDB(B1, 1, 1); PG8_SCHED; PG8_LDA(At, 1, 0); PG8_STAGE(PG8_SA(0, 1), a2 + hstep, voffA);
;             PG8_WAIT_V(8); PG8_WAIT_L(0); PG8_BAR; PG8_MMA(0, 0, At, B0); PG8_MMA(0, 1, At, B1); PG8_BAR; PG8_SCHED;
	s_setprio 1
	s_waitcnt lgkmcnt(0)
	v_mfma_f32_16x16x32_bf16 v[62:65], v[134:137], v[200:203], v[62:65]
	v_mfma_f32_16x16x32_bf16 v[58:61], v[142:145], v[200:203], v[58:61]
	v_mfma_f32_16x16x32_bf16 v[46:49], v[134:137], v[208:211], v[46:49]
	v_mfma_f32_16x16x32_bf16 v[42:45], v[142:145], v[208:211], v[42:45]
	v_mfma_f32_16x16x32_bf16 v[30:33], v[134:137], v[216:219], v[30:33]
	v_mfma_f32_16x16x32_bf16 v[26:29], v[142:145], v[216:219], v[26:29]
	v_mfma_f32_16x16x32_bf16 v[14:17], v[134:137], v[224:227], v[14:17]
	v_mfma_f32_16x16x32_bf16 v[10:13], v[142:145], v[224:227], v[10:13]
	v_mfma_f32_16x16x32_bf16 v[62:65], v[138:141], v[204:207], v[62:65]
	v_mfma_f32_16x16x32_bf16 v[58:61], v[146:149], v[204:207], v[58:61]
	v_mfma_f32_16x16x32_bf16 v[46:49], v[138:141], v[212:215], v[46:49]
	v_mfma_f32_16x16x32_bf16 v[42:45], v[146:149], v[212:215], v[42:45]
	v_mfma_f32_16x16x32_bf16 v[30:33], v[138:141], v[220:223], v[30:33]
	v_mfma_f32_16x16x32_bf16 v[26:29], v[146:149], v[220:223], v[26:29]
	v_mfma_f32_16x16x32_bf16 v[14:17], v[138:141], v[228:231], v[14:17]
	v_mfma_f32_16x16x32_bf16 v[10:13], v[146:149], v[228:231], v[10:13]
	s_setprio 0
	s_setprio 1
	v_mfma_f32_16x16x32_bf16 v[54:57], v[166:169], v[200:203], v[54:57]
	v_mfma_f32_16x16x32_bf16 v[50:53], v[174:177], v[200:203], v[50:53]
	v_mfma_f32_16x16x32_bf16 v[38:41], v[166:169], v[208:211], v[38:41]
	v_mfma_f32_16x16x32_bf16 v[34:37], v[174:177], v[208:211], v[34:37]
	v_mfma_f32_16x16x32_bf16 v[22:25], v[166:169], v[216:219], v[22:25]
	v_mfma_f32_16x16x32_bf16 v[18:21], v[174:177], v[216:219], v[18:21]
	v_mfma_f32_16x16x32_bf16 v[6:9], v[166:169], v[224:227], v[6:9]
	v_mfma_f32_16x16x32_bf16 v[2:5], v[174:177], v[224:227], v[2:5]
	v_mfma_f32_16x16x32_bf16 v[54:57], v[170:173], v[204:207], v[54:57]
	v_mfma_f32_16x16x32_bf16 v[50:53], v[182:185], v[204:207], v[50:53]
	v_mfma_f32_16x16x32_bf16 v[38:41], v[170:173], v[212:215], v[38:41]
	v_mfma_f32_16x16x32_bf16 v[34:37], v[182:185], v[212:215], v[34:37]
	v_mfma_f32_16x16x32_bf16 v[22:25], v[170:173], v[220:223], v[22:25]
	v_mfma_f32_16x16x32_bf16 v[18:21], v[182:185], v[220:223], v[18:21]
	v_mfma_f32_16x16x32_bf16 v[6:9], v[170:173], v[228:231], v[6:9]
	v_mfma_f32_16x16x32_bf16 v[2:5], v[182:185], v[228:231], v[2:5]
	s_setprio 0
	s_barrier
	s_add_i32 s80, 0, 0x18000
	s_add_i32 s81, 0, 0x1c000
	v_add_u32_e32 v146, s80, v159
	v_add_u32_e32 v182, s81, v159
	ds_read_b128 v[134:137], v146
	ds_read_b128 v[138:141], v146 offset:1024
	ds_read_b128 v[142:145], v146 offset:2048
	ds_read_b128 v[146:149], v146 offset:3072
	ds_read_b128 v[166:169], v182
	ds_read_b128 v[170:173], v182 offset:1024
	ds_read_b128 v[174:177], v182 offset:2048
	ds_read_b128 v[182:185], v182 offset:3072
	s_add_u32 s78, s78, 0x40000
	s_addc_u32 s79, s79, 0
	s_mov_b32 m0, s48
	v_lshl_add_u64 v[238:239], s[78:79], 0, v[150:151]
	ds_read_b128 v[200:203], v180 offset:32768
	ds_read_b128 v[204:207], v180 offset:33792
	ds_read_b128 v[208:211], v180 offset:34816
	ds_read_b128 v[212:215], v180 offset:35840
	ds_read_b128 v[216:219], v180 offset:36864
	ds_read_b128 v[220:223], v180 offset:37888
	ds_read_b128 v[224:227], v180 offset:38912
	ds_read_b128 v[228:231], v180 offset:39936
	global_load_lds_dwordx4 v[238:239], off
	v_lshl_add_u64 v[238:239], s[78:79], 0, v[154:155]
	s_mov_b32 m0, s49
	s_nop 0
	global_load_lds_dwordx4 v[238:239], off
	s_waitcnt vmcnt(8)
	s_waitcnt lgkmcnt(0)
	s_barrier
	s_setprio 1
	s_waitcnt lgkmcnt(0)
	v_mfma_f32_16x16x32_bf16 v[130:133], v[134:137], v[200:203], v[130:133]
	v_mfma_f32_16x16x32_bf16 v[126:129], v[142:145], v[200:203], v[126:129]
	v_mfma_f32_16x16x32_bf16 v[114:117], v[134:137], v[208:211], v[114:117]
	v_mfma_f32_16x16x32_bf16 v[110:113], v[142:145], v[208:211], v[110:113]
	v_mfma_f32_16x16x32_bf16 v[98:101], v[134:137], v[216:219], v[98:101]
	v_mfma_f32_16x16x32_bf16 v[94:97], v[142:145], v[216:219], v[94:97]
	v_mfma_f32_16x16x32_bf16 v[78:81], v[134:137], v[224:227], v[78:81]
	v_mfma_f32_16x16x32_bf16 v[74:77], v[142:145], v[224:227], v[74:77]
	v_mfma_f32_16x16x32_bf16 v[130:133], v[138:141], v[204:207], v[130:133]
	v_mfma_f32_16x16x32_bf16 v[126:129], v[146:149], v[204:207], v[126:129]
	v_mfma_f32_16x16x32_bf16 v[114:117], v[138:141], v[212:215], v[114:117]
	v_mfma_f32_16x16x32_bf16 v[110:113], v[146:149], v[212:215], v[110:113]
	v_mfma_f32_16x16x32_bf16 v[98:101], v[138:141], v[220:223], v[98:101]
	v_mfma_f32_16x16x32_bf16 v[94:97], v[146:149], v[220:223], v[94:97]
	v_mfma_f32_16x16x32_bf16 v[78:81], v[138:141], v[228:231], v[78:81]
	v_mfma_f32_16x16x32_bf16 v[74:77], v[146:149], v[228:231], v[74:77]
	s_setprio 0
	s_setprio 1
	v_mfma_f32_16x16x32_bf16 v[122:125], v[166:169], v[200:203], v[122:125]
	v_mfma_f32_16x16x32_bf16 v[118:121], v[174:177], v[200:203], v[118:121]
	v_mfma_f32_16x16x32_bf16 v[106:109], v[166:169], v[208:211], v[106:109]
	v_mfma_f32_16x16x32_bf16 v[102:105], v[174:177], v[208:211], v[102:105]
	v_mfma_f32_16x16x32_bf16 v[90:93], v[166:169], v[216:219], v[90:93]
	v_mfma_f32_16x16x32_bf16 v[86:89], v[174:177], v[216:219], v[86:89]
	v_mfma_f32_16x16x32_bf16 v[70:73], v[166:169], v[224:227], v[70:73]
	v_mfma_f32_16x16x32_bf16 v[66:69], v[174:177], v[224:227], v[66:69]
	v_mfma_f32_16x16x32_bf16 v[122:125], v[170:173], v[204:207], v[122:125]
	v_mfma_f32_16x16x32_bf16 v[118:121], v[182:185], v[204:207], v[118:121]
	v_mfma_f32_16x16x32_bf16 v[106:109], v[170:173], v[212:215], v[106:109]
	v_mfma_f32_16x16x32_bf16 v[102:105], v[182:185], v[212:215], v[102:105]
	v_mfma_f32_16x16x32_bf16 v[90:93], v[170:173], v[220:223], v[90:93]
	v_mfma_f32_16x16x32_bf16 v[86:89], v[182:185], v[220:223], v[86:89]
	v_mfma_f32_16x16x32_bf16 v[70:73], v[170:173], v[228:231], v[70:73]
	v_mfma_f32_16x16x32_bf16 v[66:69], v[182:185], v[228:231], v[66:69]
	s_setprio 0
	s_barrier
; #define PG8_STAGE(bufoff, gbase, voff) do { _Pragma("unroll") for (int _i = 0; _i < 2; ++_i) \
;         __builtin_amdgcn_global_load_lds((const unsigned*)((const char*)(gbase) + (voff)[_i]), (PG8_LAS unsigned*)(lds + (bufoff) + ldsw + _i * 8192), 16, 0, 0); } while (0)
; #define PG8_LDA(dst, b, h) do { _Pragma("unroll") for (int m = 0; m < 4; ++m) _Pragma("unroll") for (int k = 0; k < 2; ++k) dst[m][k] = *(const PG8_LAS bf16x8*)(lds + PG8_SA(b, h) + aoff + m * 2048 + k * 1024); } while (0)
; #define PG8_MMA(ai, bj, At, Bt) do { __builtin_amdgcn_s_setprio(1); _Pragma("unroll") for (int m = 0; m < 4; ++m) _Pragma("unroll") for (int n = 0; n < 2; ++n) _Pragma("unroll") for (int k = 0; k < 2; ++k) \
;         acc[ai][bj][m][n] = __builtin_amdgcn_mfma_f32_16x16x32_bf16(Bt[n][k], At[m][k], acc[ai][bj][m][n], 0, 0, 0); __builtin_amdgcn_s_setprio(0); } while (0)
; #define PG8_WAIT_V(n) asm volatile("s_waitcnt vmcnt(" #n ")" ::: "memory")
; #define PG8_WAIT_L(n) asm volatile("s_waitcnt lgkmcnt(" #n ")" ::: "memory")
; #define PG8_BAR __builtin_amdgcn_s_barrier()
; #define PG8_SCHED __builtin_amdgcn_sched_barrier(0)
; template <class Epi, class Sched, bool ALIGN_EPI = false, bool SP2 = false>
; __device__ __forceinline__ void gemm_phase(PG8_LAS unsigned char* lds, const Gemm g, const Sched& S, const Epi& E) {
;     ...
;         for (int t = 0; t < nt; t += 2) {
;             const bool last = (t == nt - 2);
;             const char* a1 = cA + (size_t)(t + 1) * kstep;
;             const char* a2 = last ? nA : cA + (size_t)(t + 2) * kstep; const char* b2 = last ? nB : cB + (size_t)(t + 2) * kstep;
;             const char* a3 = a2 + kstep; const char* b3 = b2 + kstep;
;     ...
;             PG8_LDA(At, 1, 1); PG8_STAGE(PG8_SB(1, 0), b3, voffB); PG8_STAGE(PG8_SB(1, 1), b3 + hstep, voffB); PG8_STAGE(PG8_SA(1, 0), a3, voffA);
;             PG8_WAIT_V(8); PG8_WAIT_L(0); PG8_BAR; PG8_MMA(1, 0, At, B0); PG8_MMA(1, 1, At, B1); PG8_BAR; PG8_SCHED;
	s_add_i32 s78, s80, s36
	v_lshl_add_u64 v[186:187], v[186:187], 0, s[38:39]
	s_mov_b32 m0, s78
	ds_read_b128 v[200:203], v180 offset:49152
	ds_read_b128 v[204:207], v180 offset:50176
	ds_read_b128 v[208:211], v180 offset:51200
	ds_read_b128 v[212:215], v180 offset:52224
	ds_read_b128 v[216:219], v180 offset:53248
	ds_read_b128 v[220:223], v180 offset:54272
	ds_read_b128 v[224:227], v180 offset:55296
	ds_read_b128 v[228:231], v180 offset:56320
	global_load_lds_dwordx4 v[186:187], off
	s_add_i32 m0, s78, 0x2000
	s_add_u32 s76, s76, 0x40080
	v_lshl_add_u64 v[186:187], v[232:233], 0, s[38:39]
	s_addc_u32 s77, s77, 0
	s_add_i32 s78, s81, s36
	global_load_lds_dwordx4 v[186:187], off
	v_lshl_add_u64 v[186:187], s[76:77], 0, v[152:153]
	s_mov_b32 m0, s78
	s_nop 0
	global_load_lds_dwordx4 v[186:187], off
	v_lshl_add_u64 v[186:187], s[76:77], 0, v[156:157]
	s_add_i32 m0, s78, 0x2000
	s_nop 0
	global_load_lds_dwordx4 v[186:187], off
	v_lshl_add_u64 v[186:187], v[234:235], 0, s[38:39]
	s_mov_b32 m0, s56
	s_nop 0
	global_load_lds_dwordx4 v[186:187], off
	v_lshl_add_u64 v[186:187], v[236:237], 0, s[38:39]
	s_mov_b32 m0, s75
	s_nop 0
	global_load_lds_dwordx4 v[186:187], off
	s_waitcnt vmcnt(8)
	s_waitcnt lgkmcnt(0)
	s_barrier
	s_setprio 1
	s_waitcnt lgkmcnt(0)
	v_mfma_f32_16x16x32_bf16 v[62:65], v[134:137], v[200:203], v[62:65]
	v_mfma_f32_16x16x32_bf16 v[58:61], v[142:145], v[200:203], v[58:61]
	v_mfma_f32_16x16x32_bf16 v[46:49], v[134:137], v[208:211], v[46:49]
	v_mfma_f32_16x16x32_bf16 v[42:45], v[142:145], v[208:211], v[42:45]
	v_mfma_f32_16x16x32_bf16 v[30:33], v[134:137], v[216:219], v[30:33]
	v_mfma_f32_16x16x32_bf16 v[26:29], v[142:145], v[216:219], v[26:29]
	v_mfma_f32_16x16x32_bf16 v[14:17], v[134:137], v[224:227], v[14:17]
	v_mfma_f32_16x16x32_bf16 v[10:13], v[142:145], v[224:227], v[10:13]
	v_mfma_f32_16x16x32_bf16 v[62:65], v[138:141], v[204:207], v[62:65]
	v_mfma_f32_16x16x32_bf16 v[58:61], v[146:149], v[204:207], v[58:61]
	v_mfma_f32_16x16x32_bf16 v[46:49], v[138:141], v[212:215], v[46:49]
	v_mfma_f32_16x16x32_bf16 v[42:45], v[146:149], v[212:215], v[42:45]
	v_mfma_f32_16x16x32_bf16 v[30:33], v[138:141], v[220:223], v[30:33]
	v_mfma_f32_16x16x32_bf16 v[26:29], v[146:149], v[220:223], v[26:29]
	v_mfma_f32_16x16x32_bf16 v[14:17], v[138:141], v[228:231], v[14:17]
	v_mfma_f32_16x16x32_bf16 v[10:13], v[146:149], v[228:231], v[10:13]
	s_setprio 0
	s_setprio 1
	v_mfma_f32_16x16x32_bf16 v[54:57], v[166:169], v[200:203], v[54:57]
	v_mfma_f32_16x16x32_bf16 v[50:53], v[174:177], v[200:203], v[50:53]
	v_mfma_f32_16x16x32_bf16 v[38:41], v[166:169], v[208:211], v[38:41]
	v_mfma_f32_16x16x32_bf16 v[34:37], v[174:177], v[208:211], v[34:37]
	v_mfma_f32_16x16x32_bf16 v[22:25], v[166:169], v[216:219], v[22:25]
	v_mfma_f32_16x16x32_bf16 v[18:21], v[174:177], v[216:219], v[18:21]
	v_mfma_f32_16x16x32_bf16 v[6:9], v[166:169], v[224:227], v[6:9]
	v_mfma_f32_16x16x32_bf16 v[2:5], v[174:177], v[224:227], v[2:5]
	v_mfma_f32_16x16x32_bf16 v[54:57], v[170:173], v[204:207], v[54:57]
	v_mfma_f32_16x16x32_bf16 v[50:53], v[182:185], v[204:207], v[50:53]
	v_mfma_f32_16x16x32_bf16 v[38:41], v[170:173], v[212:215], v[38:41]
	v_mfma_f32_16x16x32_bf16 v[34:37], v[182:185], v[212:215], v[34:37]
	v_mfma_f32_16x16x32_bf16 v[22:25], v[170:173], v[220:223], v[22:25]
	v_mfma_f32_16x16x32_bf16 v[18:21], v[182:185], v[220:223], v[18:21]
	v_mfma_f32_16x16x32_bf16 v[6:9], v[170:173], v[228:231], v[6:9]
	v_mfma_f32_16x16x32_bf16 v[2:5], v[182:185], v[228:231], v[2:5]
	s_setprio 0
	s_add_i32 s69, s69, 2
	s_add_u32 s41, s41, 0x100
	s_addc_u32 s67, s67, 0
	s_add_u32 s12, s12, 0x100
	s_addc_u32 s13, s13, 0
	s_cmp_gt_u32 s69, 13
	s_cbranch_scc1 .Lk_p1_exit
	s_add_u32 s76, s12, 0xfffc0080
	s_addc_u32 s77, s13, -1
	s_add_i32 s80, 0, 0x10000
	s_cmp_eq_u32 s69, 12
	s_cselect_b32 s79, s11, s77
	s_cselect_b32 s78, s22, s76
	s_cselect_b32 s77, s23, s67
	s_cselect_b32 s76, s40, s41
	s_add_i32 s86, 0, 0x14000
	v_add_u32_e32 v146, s80, v159
	v_add_u32_e32 v182, s86, v159
	s_branch .Lk_p1_head
.Lk_p1_exit:
	s_barrier
	s_and_b64 vcc, exec, s[64:65]
	s_cbranch_vccz .LBB0_114
	s_barrier

; template <class Epi, class Sched, bool ALIGN_EPI = false, bool SP2 = false>
; __device__ __forceinline__ void gemm_phase(PG8_LAS unsigned char* lds, const Gemm g, const Sched& S, const Epi& E) {
;     ...
;         for (int t = 0; t < nt; t += 2) {
;             const bool last = (t == nt - 2);
;             const char* a1 = cA + (size_t)(t + 1) * kstep;
;             const char* a2 = last ? nA : cA + (size_t)(t + 2) * kstep; const char* b2 = last ? nB : cB + (size_t)(t + 2) * kstep;
;             const char* a3 = a2 + kstep; const char* b3 = b2 + kstep;
.LBB0_684:
	s_add_u32 s24, s20, 0x100
	s_addc_u32 s25, s21, 0
	s_add_i32 s63, 0, 0x10000
	s_cmp_eq_u32 s62, 16
	s_cselect_b32 s59, s7, s25
	s_cselect_b32 s58, s6, s24
	v_add_u32_e32 v150, s63, v152
	s_cselect_b32 s27, s19, s61
	s_cselect_b32 s26, s18, s41
	s_add_i32 s64, 0, 0x14000
	s_branch .Lk_p3a1_body

; #define PG8_STAGE(bufoff, gbase, voff) do { _Pragma("unroll") for (int _i = 0; _i < 2; ++_i) \
;         __builtin_amdgcn_global_load_lds((const unsigned*)((const char*)(gbase) + (voff)[_i]), (PG8_LAS unsigned*)(lds + (bufoff) + ldsw + _i * 8192), 16, 0, 0); } while (0)
; #define PG8_LDA(dst, b, h) do { _Pragma("unroll") for (int m = 0; m < 4; ++m) _Pragma("unroll") for (int k = 0; k < 2; ++k) dst[m][k] = *(const PG8_LAS bf16x8*)(lds + PG8_SA(b, h) + aoff + m * 2048 + k * 1024); } while (0)
; #define PG8_LDB(dst, b, h) do { _Pragma("unroll") for (int n = 0; n < 2; ++n) _Pragma("unroll") for (int k = 0; k < 2; ++k) dst[n][k] = *(const PG8_LAS bf16x8*)(lds + PG8_SB(b, h) + boff + n * 2048 + k * 1024); } while (0)
; #define PG8_MMA(ai, bj, At, Bt) do { __builtin_amdgcn_s_setprio(1); _Pragma("unroll") for (int m = 0; m < 4; ++m) _Pragma("unroll") for (int n = 0; n < 2; ++n) _Pragma("unroll") for (int k = 0; k < 2; ++k) \
;         acc[ai][bj][m][n] = __builtin_amdgcn_mfma_f32_16x16x32_bf16(Bt[n][k], At[m][k], acc[ai][bj][m][n], 0, 0, 0); __builtin_amdgcn_s_setprio(0); } while (0)
; #define PG8_WAIT_V(n) asm volatile("s_waitcnt vmcnt(" #n ")" ::: "memory")
; #define PG8_WAIT_L(n) asm volatile("s_waitcnt lgkmcnt(" #n ")" ::: "memory")
; #define PG8_BAR __builtin_amdgcn_s_barrier()
; #define PG8_SCHED __builtin_amdgcn_sched_barrier(0)
; template <class Epi, class Sched, bool ALIGN_EPI = false, bool SP2 = false>
; __device__ __forceinline__ void gemm_phase(PG8_LAS unsigned char* lds, const Gemm g, const Sched& S, const Epi& E) {
;     ...
;             PG8_LDB(B0, 0, 0); PG8_LDB(B1, 0, 1); PG8_SCHED; PG8_LDA(At, 0, 0); PG8_STAGE(PG8_SA(1, 1), a1 + hstep, voffA);
;             PG8_WAIT_V(8); PG8_WAIT_L(0); PG8_BAR; PG8_MMA(0, 0, At, B0); PG8_MMA(0, 1, At, B1); PG8_BAR; PG8_SCHED;
;             PG8_LDA(At, 0, 1); PG8_STAGE(PG8_SB(0, 0), b2, voffB); PG8_STAGE(PG8_SB(0, 1), b2 + hstep, voffB); PG8_STAGE(PG8_SA(0, 0), a2, voffA);
;             PG8_WAIT_V(8); PG8_WAIT_L(0); PG8_BAR; PG8_MMA(1, 0, At, B0); PG8_MMA(1, 1, At, B1); PG8_BAR; PG8_SCHED;
.Lk_p3a1_body:
	ds_read_b128 v[146:149], v150
	ds_read_b128 v[156:159], v150 offset:1024
	ds_read_b128 v[160:163], v150 offset:2048
	ds_read_b128 v[164:167], v150 offset:3072
	v_add_u32_e32 v150, s64, v152
	ds_read_b128 v[168:171], v150
	ds_read_b128 v[172:175], v150 offset:1024
	ds_read_b128 v[180:183], v150 offset:2048
	ds_read_b128 v[184:187], v150 offset:3072
	v_lshl_add_u64 v[150:151], s[20:21], 0, v[144:145]
	s_add_i32 m0, s42, 0xc000
	ds_read_b128 v[200:203], v154
	ds_read_b128 v[204:207], v154 offset:1024
	ds_read_b128 v[208:211], v154 offset:2048
	ds_read_b128 v[212:215], v154 offset:3072
	ds_read_b128 v[216:219], v154 offset:4096
	ds_read_b128 v[220:223], v154 offset:5120
	ds_read_b128 v[224:227], v154 offset:6144
	ds_read_b128 v[228:231], v154 offset:7168
	global_load_lds_dwordx4 v[150:151], off
	v_lshl_add_u64 v[150:151], s[20:21], 0, v[142:143]
	s_add_i32 m0, s42, 0xe000
	s_nop 0
	global_load_lds_dwordx4 v[150:151], off
	s_waitcnt vmcnt(8)
	s_waitcnt lgkmcnt(0)
	s_barrier
	s_setprio 1
	s_waitcnt lgkmcnt(0)
	v_mfma_f32_16x16x32_bf16 v[130:133], v[146:149], v[200:203], v[130:133]
	v_mfma_f32_16x16x32_bf16 v[126:129], v[160:163], v[200:203], v[126:129]
	v_mfma_f32_16x16x32_bf16 v[114:117], v[146:149], v[208:211], v[114:117]
	v_mfma_f32_16x16x32_bf16 v[110:113], v[160:163], v[208:211], v[110:113]
	v_mfma_f32_16x16x32_bf16 v[98:101], v[146:149], v[216:219], v[98:101]
	v_mfma_f32_16x16x32_bf16 v[94:97], v[160:163], v[216:219], v[94:97]
	v_mfma_f32_16x16x32_bf16 v[78:81], v[146:149], v[224:227], v[78:81]
	v_mfma_f32_16x16x32_bf16 v[74:77], v[160:163], v[224:227], v[74:77]
	v_mfma_f32_16x16x32_bf16 v[130:133], v[156:159], v[204:207], v[130:133]
	v_mfma_f32_16x16x32_bf16 v[126:129], v[164:167], v[204:207], v[126:129]
	v_mfma_f32_16x16x32_bf16 v[114:117], v[156:159], v[212:215], v[114:117]
	v_mfma_f32_16x16x32_bf16 v[110:113], v[164:167], v[212:215], v[110:113]
	v_mfma_f32_16x16x32_bf16 v[98:101], v[156:159], v[220:223], v[98:101]
	v_mfma_f32_16x16x32_bf16 v[94:97], v[164:167], v[220:223], v[94:97]
	v_mfma_f32_16x16x32_bf16 v[78:81], v[156:159], v[228:231], v[78:81]
	v_mfma_f32_16x16x32_bf16 v[74:77], v[164:167], v[228:231], v[74:77]
	s_setprio 0
	s_setprio 1
	v_mfma_f32_16x16x32_bf16 v[122:125], v[168:171], v[200:203], v[122:125]
	v_mfma_f32_16x16x32_bf16 v[118:121], v[180:183], v[200:203], v[118:121]
	v_mfma_f32_16x16x32_bf16 v[106:109], v[168:171], v[208:211], v[106:109]
	v_mfma_f32_16x16x32_bf16 v[102:105], v[180:183], v[208:211], v[102:105]
	v_mfma_f32_16x16x32_bf16 v[90:93], v[168:171], v[216:219], v[90:93]
	v_mfma_f32_16x16x32_bf16 v[86:89], v[180:183], v[216:219], v[86:89]
	v_mfma_f32_16x16x32_bf16 v[70:73], v[168:171], v[224:227], v[70:73]
	v_mfma_f32_16x16x32_bf16 v[66:69], v[180:183], v[224:227], v[66:69]
	v_mfma_f32_16x16x32_bf16 v[122:125], v[172:175], v[204:207], v[122:125]
	v_mfma_f32_16x16x32_bf16 v[118:121], v[184:187], v[204:207], v[118:121]
	v_mfma_f32_16x16x32_bf16 v[106:109], v[172:175], v[212:215], v[106:109]
	v_mfma_f32_16x16x32_bf16 v[102:105], v[184:187], v[212:215], v[102:105]
	v_mfma_f32_16x16x32_bf16 v[90:93], v[172:175], v[220:223], v[90:93]
	v_mfma_f32_16x16x32_bf16 v[86:89], v[184:187], v[220:223], v[86:89]
	v_mfma_f32_16x16x32_bf16 v[70:73], v[172:175], v[228:231], v[70:73]
	v_mfma_f32_16x16x32_bf16 v[66:69], v[184:187], v[228:231], v[66:69]
	s_setprio 0
	s_barrier
	s_add_i32 s20, s63, s29
	v_lshl_add_u64 v[150:151], s[26:27], 0, v[138:139]
	s_mov_b32 m0, s20
	ds_read_b128 v[200:203], v154 offset:16384
	ds_read_b128 v[204:207], v154 offset:17408
	ds_read_b128 v[208:211], v154 offset:18432
	ds_read_b128 v[212:215], v154 offset:19456
	ds_read_b128 v[216:219], v154 offset:20480
	ds_read_b128 v[220:223], v154 offset:21504
	ds_read_b128 v[224:227], v154 offset:22528
	ds_read_b128 v[228:231], v154 offset:23552
	global_load_lds_dwordx4 v[150:151], off
	s_add_i32 m0, s20, 0x2000
	s_add_u32 s20, s26, 0x50000
	v_lshl_add_u64 v[176:177], s[26:27], 0, v[134:135]
	s_addc_u32 s21, s27, 0
	s_add_i32 s63, s64, s29
	global_load_lds_dwordx4 v[176:177], off
	v_lshl_add_u64 v[232:233], s[20:21], 0, v[138:139]
	s_mov_b32 m0, s63
	v_lshl_add_u64 v[234:235], s[58:59], 0, v[136:137]
	global_load_lds_dwordx4 v[232:233], off
	v_lshl_add_u64 v[232:233], s[20:21], 0, v[134:135]
	s_add_i32 m0, s63, 0x2000
	s_nop 0
	global_load_lds_dwordx4 v[232:233], off
	v_lshl_add_u64 v[232:233], s[58:59], 0, v[140:141]
	s_mov_b32 m0, s42
	s_nop 0
	global_load_lds_dwordx4 v[232:233], off
	s_mov_b32 m0, s48
	s_nop 0
	global_load_lds_dwordx4 v[234:235], off
	s_waitcnt vmcnt(8)
	s_waitcnt lgkmcnt(0)
	s_barrier
; #define PG8_STAGE(bufoff, gbase, voff) do { _Pragma("unroll") for (int _i = 0; _i < 2; ++_i) \
;         __builtin_amdgcn_global_load_lds((const unsigned*)((const char*)(gbase) + (voff)[_i]), (PG8_LAS unsigned*)(lds + (bufoff) + ldsw + _i * 8192), 16, 0, 0); } while (0)
; #define PG8_LDA(dst, b, h) do { _Pragma("unroll") for (int m = 0; m < 4; ++m) _Pragma("unroll") for (int k = 0; k < 2; ++k) dst[m][k] = *(const PG8_LAS bf16x8*)(lds + PG8_SA(b, h) + aoff + m * 2048 + k * 1024); } while (0)
; #define PG8_LDB(dst, b, h) do { _Pragma("unroll") for (int n = 0; n < 2; ++n) _Pragma("unroll") for (int k = 0; k < 2; ++k) dst[n][k] = *(const PG8_LAS bf16x8*)(lds + PG8_SB(b, h) + boff + n * 2048 + k * 1024); } while (0)
; #define PG8_MMA(ai, bj, At, Bt) do { __builtin_amdgcn_s_setprio(1); _Pragma("unroll") for (int m = 0; m < 4; ++m) _Pragma("unroll") for (int n = 0; n < 2; ++n) _Pragma("unroll") for (int k = 0; k < 2; ++k) \
;         acc[ai][bj][m][n] = __builtin_amdgcn_mfma_f32_16x16x32_bf16(Bt[n][k], At[m][k], acc[ai][bj][m][n], 0, 0, 0); __builtin_amdgcn_s_setprio(0); } while (0)
; #define PG8_WAIT_V(n) asm volatile("s_waitcnt vmcnt(" #n ")" ::: "memory")
; #define PG8_WAIT_L(n) asm volatile("s_waitcnt lgkmcnt(" #n ")" ::: "memory")
; #define PG8_BAR __builtin_amdgcn_s_barrier()
; #define PG8_SCHED __builtin_amdgcn_sched_barrier(0)
; template <class Epi, class Sched, bool ALIGN_EPI = false, bool SP2 = false>
; __device__ __forceinline__ void gemm_phase(PG8_LAS unsigned char* lds, const Gemm g, const Sched& S, const Epi& E) {
;     ...
;             PG8_WAIT_V(8); PG8_WAIT_L(0); PG8_BAR; PG8_MMA(1, 0, At, B0); PG8_MMA(1, 1, At, B1); PG8_BAR; PG8_SCHED;
;             PG8_LDB(B0, 1, 0); PG8_LDB(B1, 1, 1); PG8_SCHED; PG8_LDA(At, 1, 0); PG8_STAGE(PG8_SA(0, 1), a2 + hstep, voffA);
;             PG8_WAIT_V(8); PG8_WAIT_L(0); PG8_BAR; PG8_MMA(0, 0, At, B0); PG8_MMA(0, 1, At, B1); PG8_BAR; PG8_SCHED;
	s_setprio 1
	s_waitcnt lgkmcnt(0)
	v_mfma_f32_16x16x32_bf16 v[62:65], v[146:149], v[200:203], v[62:65]
	v_mfma_f32_16x16x32_bf16 v[58:61], v[160:163], v[200:203], v[58:61]
	v_mfma_f32_16x16x32_bf16 v[46:49], v[146:149], v[208:211], v[46:49]
	v_mfma_f32_16x16x32_bf16 v[42:45], v[160:163], v[208:211], v[42:45]
	v_mfma_f32_16x16x32_bf16 v[30:33], v[146:149], v[216:219], v[30:33]
	v_mfma_f32_16x16x32_bf16 v[26:29], v[160:163], v[216:219], v[26:29]
	v_mfma_f32_16x16x32_bf16 v[14:17], v[146:149], v[224:227], v[14:17]
	v_mfma_f32_16x16x32_bf16 v[10:13], v[160:163], v[224:227], v[10:13]
	v_mfma_f32_16x16x32_bf16 v[62:65], v[156:159], v[204:207], v[62:65]
	v_mfma_f32_16x16x32_bf16 v[58:61], v[164:167], v[204:207], v[58:61]
	v_mfma_f32_16x16x32_bf16 v[46:49], v[156:159], v[212:215], v[46:49]
	v_mfma_f32_16x16x32_bf16 v[42:45], v[164:167], v[212:215], v[42:45]
	v_mfma_f32_16x16x32_bf16 v[30:33], v[156:159], v[220:223], v[30:33]
	v_mfma_f32_16x16x32_bf16 v[26:29], v[164:167], v[220:223], v[26:29]
	v_mfma_f32_16x16x32_bf16 v[14:17], v[156:159], v[228:231], v[14:17]
	v_mfma_f32_16x16x32_bf16 v[10:13], v[164:167], v[228:231], v[10:13]
	s_setprio 0
	s_setprio 1
	v_mfma_f32_16x16x32_bf16 v[54:57], v[168:171], v[200:203], v[54:57]
	v_mfma_f32_16x16x32_bf16 v[50:53], v[180:183], v[200:203], v[50:53]
	v_mfma_f32_16x16x32_bf16 v[38:41], v[168:171], v[208:211], v[38:41]
	v_mfma_f32_16x16x32_bf16 v[34:37], v[180:183], v[208:211], v[34:37]
	v_mfma_f32_16x16x32_bf16 v[22:25], v[168:171], v[216:219], v[22:25]
	v_mfma_f32_16x16x32_bf16 v[18:21], v[180:183], v[216:219], v[18:21]
	v_mfma_f32_16x16x32_bf16 v[6:9], v[168:171], v[224:227], v[6:9]
	v_mfma_f32_16x16x32_bf16 v[2:5], v[180:183], v[224:227], v[2:5]
	v_mfma_f32_16x16x32_bf16 v[54:57], v[172:175], v[204:207], v[54:57]
	v_mfma_f32_16x16x32_bf16 v[50:53], v[184:187], v[204:207], v[50:53]
	v_mfma_f32_16x16x32_bf16 v[38:41], v[172:175], v[212:215], v[38:41]
	v_mfma_f32_16x16x32_bf16 v[34:37], v[184:187], v[212:215], v[34:37]
	v_mfma_f32_16x16x32_bf16 v[22:25], v[172:175], v[220:223], v[22:25]
	v_mfma_f32_16x16x32_bf16 v[18:21], v[184:187], v[220:223], v[18:21]
	v_mfma_f32_16x16x32_bf16 v[6:9], v[172:175], v[228:231], v[6:9]
	v_mfma_f32_16x16x32_bf16 v[2:5], v[184:187], v[228:231], v[2:5]
	s_setprio 0
	s_barrier
	s_add_i32 s63, 0, 0x18000
	v_add_u32_e32 v155, s63, v152
	s_add_i32 s64, 0, 0x1c000
	ds_read_b128 v[146:149], v155
	ds_read_b128 v[156:159], v155 offset:1024
	ds_read_b128 v[160:163], v155 offset:2048
	ds_read_b128 v[164:167], v155 offset:3072
	v_add_u32_e32 v155, s64, v152
	ds_read_b128 v[168:171], v155
	ds_read_b128 v[172:175], v155 offset:1024
	ds_read_b128 v[180:183], v155 offset:2048
	ds_read_b128 v[184:187], v155 offset:3072
	s_add_u32 s20, s58, 0x50000
	s_addc_u32 s21, s59, 0
	s_mov_b32 m0, s49
	v_lshl_add_u64 v[236:237], s[20:21], 0, v[140:141]
	ds_read_b128 v[200:203], v154 offset:32768
	ds_read_b128 v[204:207], v154 offset:33792
	ds_read_b128 v[208:211], v154 offset:34816
	ds_read_b128 v[212:215], v154 offset:35840
	ds_read_b128 v[216:219], v154 offset:36864
	ds_read_b128 v[220:223], v154 offset:37888
	ds_read_b128 v[224:227], v154 offset:38912
	ds_read_b128 v[228:231], v154 offset:39936
	global_load_lds_dwordx4 v[236:237], off
	v_lshl_add_u64 v[236:237], s[20:21], 0, v[136:137]
	s_mov_b32 m0, s52
	s_nop 0
	global_load_lds_dwordx4 v[236:237], off
	s_waitcnt vmcnt(8)
	s_waitcnt lgkmcnt(0)
	s_barrier
	s_setprio 1
	s_waitcnt lgkmcnt(0)
	v_mfma_f32_16x16x32_bf16 v[130:133], v[146:149], v[200:203], v[130:133]
	v_mfma_f32_16x16x32_bf16 v[126:129], v[160:163], v[200:203], v[126:129]
	v_mfma_f32_16x16x32_bf16 v[114:117], v[146:149], v[208:211], v[114:117]
	v_mfma_f32_16x16x32_bf16 v[110:113], v[160:163], v[208:211], v[110:113]
	v_mfma_f32_16x16x32_bf16 v[98:101], v[146:149], v[216:219], v[98:101]
	v_mfma_f32_16x16x32_bf16 v[94:97], v[160:163], v[216:219], v[94:97]
	v_mfma_f32_16x16x32_bf16 v[78:81], v[146:149], v[224:227], v[78:81]
	v_mfma_f32_16x16x32_bf16 v[74:77], v[160:163], v[224:227], v[74:77]
	v_mfma_f32_16x16x32_bf16 v[130:133], v[156:159], v[204:207], v[130:133]
	v_mfma_f32_16x16x32_bf16 v[126:129], v[164:167], v[204:207], v[126:129]
	v_mfma_f32_16x16x32_bf16 v[114:117], v[156:159], v[212:215], v[114:117]
	v_mfma_f32_16x16x32_bf16 v[110:113], v[164:167], v[212:215], v[110:113]
	v_mfma_f32_16x16x32_bf16 v[98:101], v[156:159], v[220:223], v[98:101]
	v_mfma_f32_16x16x32_bf16 v[94:97], v[164:167], v[220:223], v[94:97]
	v_mfma_f32_16x16x32_bf16 v[78:81], v[156:159], v[228:231], v[78:81]
	v_mfma_f32_16x16x32_bf16 v[74:77], v[164:167], v[228:231], v[74:77]
	s_setprio 0
	s_setprio 1
	v_mfma_f32_16x16x32_bf16 v[122:125], v[168:171], v[200:203], v[122:125]
	v_mfma_f32_16x16x32_bf16 v[118:121], v[180:183], v[200:203], v[118:121]
	v_mfma_f32_16x16x32_bf16 v[106:109], v[168:171], v[208:211], v[106:109]
	v_mfma_f32_16x16x32_bf16 v[102:105], v[180:183], v[208:211], v[102:105]
	v_mfma_f32_16x16x32_bf16 v[90:93], v[168:171], v[216:219], v[90:93]
	v_mfma_f32_16x16x32_bf16 v[86:89], v[180:183], v[216:219], v[86:89]
	v_mfma_f32_16x16x32_bf16 v[70:73], v[168:171], v[224:227], v[70:73]
	v_mfma_f32_16x16x32_bf16 v[66:69], v[180:183], v[224:227], v[66:69]
	v_mfma_f32_16x16x32_bf16 v[122:125], v[172:175], v[204:207], v[122:125]
	v_mfma_f32_16x16x32_bf16 v[118:121], v[184:187], v[204:207], v[118:121]
	v_mfma_f32_16x16x32_bf16 v[106:109], v[172:175], v[212:215], v[106:109]
	v_mfma_f32_16x16x32_bf16 v[102:105], v[184:187], v[212:215], v[102:105]
	v_mfma_f32_16x16x32_bf16 v[90:93], v[172:175], v[220:223], v[90:93]
	v_mfma_f32_16x16x32_bf16 v[86:89], v[184:187], v[220:223], v[86:89]
	v_mfma_f32_16x16x32_bf16 v[70:73], v[172:175], v[228:231], v[70:73]
	v_mfma_f32_16x16x32_bf16 v[66:69], v[184:187], v[228:231], v[66:69]
	s_setprio 0
	s_barrier
; #define PG8_STAGE(bufoff, gbase, voff) do { _Pragma("unroll") for (int _i = 0; _i < 2; ++_i) \
;         __builtin_amdgcn_global_load_lds((const unsigned*)((const char*)(gbase) + (voff)[_i]), (PG8_LAS unsigned*)(lds + (bufoff) + ldsw + _i * 8192), 16, 0, 0); } while (0)
; #define PG8_LDA(dst, b, h) do { _Pragma("unroll") for (int m = 0; m < 4; ++m) _Pragma("unroll") for (int k = 0; k < 2; ++k) dst[m][k] = *(const PG8_LAS bf16x8*)(lds + PG8_SA(b, h) + aoff + m * 2048 + k * 1024); } while (0)
; #define PG8_MMA(ai, bj, At, Bt) do { __builtin_amdgcn_s_setprio(1); _Pragma("unroll") for (int m = 0; m < 4; ++m) _Pragma("unroll") for (int n = 0; n < 2; ++n) _Pragma("unroll") for (int k = 0; k < 2; ++k) \
;         acc[ai][bj][m][n] = __builtin_amdgcn_mfma_f32_16x16x32_bf16(Bt[n][k], At[m][k], acc[ai][bj][m][n], 0, 0, 0); __builtin_amdgcn_s_setprio(0); } while (0)
; #define PG8_WAIT_V(n) asm volatile("s_waitcnt vmcnt(" #n ")" ::: "memory")
; #define PG8_WAIT_L(n) asm volatile("s_waitcnt lgkmcnt(" #n ")" ::: "memory")
; #define PG8_BAR __builtin_amdgcn_s_barrier()
; #define PG8_SCHED __builtin_amdgcn_sched_barrier(0)
; template <class Epi, class Sched, bool ALIGN_EPI = false, bool SP2 = false>
; __device__ __forceinline__ void gemm_phase(PG8_LAS unsigned char* lds, const Gemm g, const Sched& S, const Epi& E) {
;     ...
;         for (int t = 0; t < nt; t += 2) {
;             const bool last = (t == nt - 2);
;             const char* a1 = cA + (size_t)(t + 1) * kstep;
;             const char* a2 = last ? nA : cA + (size_t)(t + 2) * kstep; const char* b2 = last ? nB : cB + (size_t)(t + 2) * kstep;
;             const char* a3 = a2 + kstep; const char* b3 = b2 + kstep;
;     ...
;             PG8_LDA(At, 1, 1); PG8_STAGE(PG8_SB(1, 0), b3, voffB); PG8_STAGE(PG8_SB(1, 1), b3 + hstep, voffB); PG8_STAGE(PG8_SA(1, 0), a3, voffA);
;             PG8_WAIT_V(8); PG8_WAIT_L(0); PG8_BAR; PG8_MMA(1, 0, At, B0); PG8_MMA(1, 1, At, B1); PG8_BAR; PG8_SCHED;
	s_add_i32 s20, s63, s29
	v_lshl_add_u64 v[150:151], v[150:151], 0, s[38:39]
	s_mov_b32 m0, s20
	ds_read_b128 v[200:203], v154 offset:49152
	ds_read_b128 v[204:207], v154 offset:50176
	ds_read_b128 v[208:211], v154 offset:51200
	ds_read_b128 v[212:215], v154 offset:52224
	ds_read_b128 v[216:219], v154 offset:53248
	ds_read_b128 v[220:223], v154 offset:54272
	ds_read_b128 v[224:227], v154 offset:55296
	ds_read_b128 v[228:231], v154 offset:56320
	global_load_lds_dwordx4 v[150:151], off
	s_add_i32 m0, s20, 0x2000
	s_add_u32 s20, s26, 0x50080
	v_lshl_add_u64 v[150:151], v[176:177], 0, s[38:39]
	s_addc_u32 s21, s27, 0
	s_add_i32 s26, s64, s29
	global_load_lds_dwordx4 v[150:151], off
	v_lshl_add_u64 v[150:151], s[20:21], 0, v[138:139]
	s_mov_b32 m0, s26
	s_nop 0
	global_load_lds_dwordx4 v[150:151], off
	v_lshl_add_u64 v[150:151], s[20:21], 0, v[134:135]
	s_add_i32 m0, s26, 0x2000
	s_nop 0
	global_load_lds_dwordx4 v[150:151], off
	v_lshl_add_u64 v[150:151], v[232:233], 0, s[38:39]
	s_mov_b32 m0, s53
	s_nop 0
	global_load_lds_dwordx4 v[150:151], off
	v_lshl_add_u64 v[150:151], v[234:235], 0, s[38:39]
	s_mov_b32 m0, s54
	s_nop 0
	global_load_lds_dwordx4 v[150:151], off
	s_waitcnt vmcnt(8)
	s_waitcnt lgkmcnt(0)
	s_barrier
	s_setprio 1
	s_waitcnt lgkmcnt(0)
	v_mfma_f32_16x16x32_bf16 v[62:65], v[146:149], v[200:203], v[62:65]
	v_mfma_f32_16x16x32_bf16 v[58:61], v[160:163], v[200:203], v[58:61]
	v_mfma_f32_16x16x32_bf16 v[46:49], v[146:149], v[208:211], v[46:49]
	v_mfma_f32_16x16x32_bf16 v[42:45], v[160:163], v[208:211], v[42:45]
	v_mfma_f32_16x16x32_bf16 v[30:33], v[146:149], v[216:219], v[30:33]
	v_mfma_f32_16x16x32_bf16 v[26:29], v[160:163], v[216:219], v[26:29]
	v_mfma_f32_16x16x32_bf16 v[14:17], v[146:149], v[224:227], v[14:17]
	v_mfma_f32_16x16x32_bf16 v[10:13], v[160:163], v[224:227], v[10:13]
	v_mfma_f32_16x16x32_bf16 v[62:65], v[156:159], v[204:207], v[62:65]
	v_mfma_f32_16x16x32_bf16 v[58:61], v[164:167], v[204:207], v[58:61]
	v_mfma_f32_16x16x32_bf16 v[46:49], v[156:159], v[212:215], v[46:49]
	v_mfma_f32_16x16x32_bf16 v[42:45], v[164:167], v[212:215], v[42:45]
	v_mfma_f32_16x16x32_bf16 v[30:33], v[156:159], v[220:223], v[30:33]
	v_mfma_f32_16x16x32_bf16 v[26:29], v[164:167], v[220:223], v[26:29]
	v_mfma_f32_16x16x32_bf16 v[14:17], v[156:159], v[228:231], v[14:17]
	v_mfma_f32_16x16x32_bf16 v[10:13], v[164:167], v[228:231], v[10:13]
	s_setprio 0
	s_setprio 1
	v_mfma_f32_16x16x32_bf16 v[54:57], v[168:171], v[200:203], v[54:57]
	v_mfma_f32_16x16x32_bf16 v[50:53], v[180:183], v[200:203], v[50:53]
	v_mfma_f32_16x16x32_bf16 v[38:41], v[168:171], v[208:211], v[38:41]
	v_mfma_f32_16x16x32_bf16 v[34:37], v[180:183], v[208:211], v[34:37]
	v_mfma_f32_16x16x32_bf16 v[22:25], v[168:171], v[216:219], v[22:25]
	v_mfma_f32_16x16x32_bf16 v[18:21], v[180:183], v[216:219], v[18:21]
	v_mfma_f32_16x16x32_bf16 v[6:9], v[168:171], v[224:227], v[6:9]
	v_mfma_f32_16x16x32_bf16 v[2:5], v[180:183], v[224:227], v[2:5]
	v_mfma_f32_16x16x32_bf16 v[54:57], v[172:175], v[204:207], v[54:57]
	v_mfma_f32_16x16x32_bf16 v[50:53], v[184:187], v[204:207], v[50:53]
	v_mfma_f32_16x16x32_bf16 v[38:41], v[172:175], v[212:215], v[38:41]
	v_mfma_f32_16x16x32_bf16 v[34:37], v[184:187], v[212:215], v[34:37]
	v_mfma_f32_16x16x32_bf16 v[22:25], v[172:175], v[220:223], v[22:25]
	v_mfma_f32_16x16x32_bf16 v[18:21], v[184:187], v[220:223], v[18:21]
	v_mfma_f32_16x16x32_bf16 v[6:9], v[172:175], v[228:231], v[6:9]
	v_mfma_f32_16x16x32_bf16 v[2:5], v[184:187], v[228:231], v[2:5]
	s_setprio 0
	s_add_i32 s62, s62, 2
	s_add_u32 s41, s41, 0x100
	s_addc_u32 s61, s61, 0
	s_cmp_gt_u32 s62, 17
	s_mov_b64 s[20:21], s[24:25]
	s_cbranch_scc1 .Lk_p3a1_exit
	s_add_u32 s24, s20, 0x100
	s_addc_u32 s25, s21, 0
	s_add_i32 s63, 0, 0x10000
	s_cmp_eq_u32 s62, 16
	s_cselect_b32 s59, s7, s25
	s_cselect_b32 s58, s6, s24
	v_add_u32_e32 v150, s63, v152
	s_cselect_b32 s27, s19, s61
	s_cselect_b32 s26, s18, s41
	s_add_i32 s64, 0, 0x14000
	s_branch .Lk_p3a1_head
.Lk_p3a1_exit:
	s_barrier
	s_and_b64 vcc, exec, s[16:17]
	s_cbranch_vccz .LBB0_687
	s_barrier

; template <class Epi, class Sched, bool ALIGN_EPI = false, bool SP2 = false>
; __device__ __forceinline__ void gemm_phase(PG8_LAS unsigned char* lds, const Gemm g, const Sched& S, const Epi& E) {
;     ...
;         for (int t = 0; t < nt; t += 2) {
;             const bool last = (t == nt - 2);
;             const char* a1 = cA + (size_t)(t + 1) * kstep;
;             const char* a2 = last ? nA : cA + (size_t)(t + 2) * kstep; const char* b2 = last ? nB : cB + (size_t)(t + 2) * kstep;
;             const char* a3 = a2 + kstep; const char* b3 = b2 + kstep;
.LBB0_700:
	s_add_u32 s59, s60, 0xfffe0080
	s_addc_u32 s62, s61, -1
	s_add_i32 s66, 0, 0x10000
	s_cmp_eq_u32 s56, 4
	s_cselect_b32 s65, s19, s62
	s_cselect_b32 s64, s23, s59
	v_add_u32_e32 v154, s66, v156
	s_cselect_b32 s63, s17, s41
	s_cselect_b32 s62, s27, s40
	s_add_i32 s59, 0, 0x14000
	s_branch .Lk_p3a2_body

; #define PG8_STAGE(bufoff, gbase, voff) do { _Pragma("unroll") for (int _i = 0; _i < 2; ++_i) \
;         __builtin_amdgcn_global_load_lds((const unsigned*)((const char*)(gbase) + (voff)[_i]), (PG8_LAS unsigned*)(lds + (bufoff) + ldsw + _i * 8192), 16, 0, 0); } while (0)
; #define PG8_LDA(dst, b, h) do { _Pragma("unroll") for (int m = 0; m < 4; ++m) _Pragma("unroll") for (int k = 0; k < 2; ++k) dst[m][k] = *(const PG8_LAS bf16x8*)(lds + PG8_SA(b, h) + aoff + m * 2048 + k * 1024); } while (0)
; #define PG8_LDB(dst, b, h) do { _Pragma("unroll") for (int n = 0; n < 2; ++n) _Pragma("unroll") for (int k = 0; k < 2; ++k) dst[n][k] = *(const PG8_LAS bf16x8*)(lds + PG8_SB(b, h) + boff + n * 2048 + k * 1024); } while (0)
; #define PG8_MMA(ai, bj, At, Bt) do { __builtin_amdgcn_s_setprio(1); _Pragma("unroll") for (int m = 0; m < 4; ++m) _Pragma("unroll") for (int n = 0; n < 2; ++n) _Pragma("unroll") for (int k = 0; k < 2; ++k) \
;         acc[ai][bj][m][n] = __builtin_amdgcn_mfma_f32_16x16x32_bf16(Bt[n][k], At[m][k], acc[ai][bj][m][n], 0, 0, 0); __builtin_amdgcn_s_setprio(0); } while (0)
; #define PG8_WAIT_V(n) asm volatile("s_waitcnt vmcnt(" #n ")" ::: "memory")
; #define PG8_WAIT_L(n) asm volatile("s_waitcnt lgkmcnt(" #n ")" ::: "memory")
; #define PG8_BAR __builtin_amdgcn_s_barrier()
; #define PG8_SCHED __builtin_amdgcn_sched_barrier(0)
; template <class Epi, class Sched, bool ALIGN_EPI = false, bool SP2 = false>
; __device__ __forceinline__ void gemm_phase(PG8_LAS unsigned char* lds, const Gemm g, const Sched& S, const Epi& E) {
;     ...
;             PG8_LDB(B0, 0, 0); PG8_LDB(B1, 0, 1); PG8_SCHED; PG8_LDA(At, 0, 0); PG8_STAGE(PG8_SA(1, 1), a1 + hstep, voffA);
;             PG8_WAIT_V(8); PG8_WAIT_L(0); PG8_BAR; PG8_MMA(0, 0, At, B0); PG8_MMA(0, 1, At, B1); PG8_BAR; PG8_SCHED;
;             PG8_LDA(At, 0, 1); PG8_STAGE(PG8_SB(0, 0), b2, voffB); PG8_STAGE(PG8_SB(0, 1), b2 + hstep, voffB); PG8_STAGE(PG8_SA(0, 0), a2, voffA);
;             PG8_WAIT_V(8); PG8_WAIT_L(0); PG8_BAR; PG8_MMA(1, 0, At, B0); PG8_MMA(1, 1, At, B1); PG8_BAR; PG8_SCHED;
.Lk_p3a2_body:
	ds_read_b128 v[146:149], v154
	ds_read_b128 v[150:153], v154 offset:1024
	ds_read_b128 v[160:163], v154 offset:2048
	ds_read_b128 v[164:167], v154 offset:3072
	v_add_u32_e32 v154, s59, v156
	ds_read_b128 v[168:171], v154
	ds_read_b128 v[172:175], v154 offset:1024
	ds_read_b128 v[180:183], v154 offset:2048
	ds_read_b128 v[184:187], v154 offset:3072
	v_lshl_add_u64 v[154:155], s[60:61], 0, v[144:145]
	s_add_i32 m0, s42, 0xc000
	ds_read_b128 v[200:203], v158
	ds_read_b128 v[204:207], v158 offset:1024
	ds_read_b128 v[208:211], v158 offset:2048
	ds_read_b128 v[212:215], v158 offset:3072
	ds_read_b128 v[216:219], v158 offset:4096
	ds_read_b128 v[220:223], v158 offset:5120
	ds_read_b128 v[224:227], v158 offset:6144
	ds_read_b128 v[228:231], v158 offset:7168
	global_load_lds_dwordx4 v[154:155], off
	v_lshl_add_u64 v[154:155], s[60:61], 0, v[142:143]
	s_add_i32 m0, s42, 0xe000
	s_nop 0
	global_load_lds_dwordx4 v[154:155], off
	s_waitcnt vmcnt(8)
	s_waitcnt lgkmcnt(0)
	s_barrier
	s_setprio 1
	s_waitcnt lgkmcnt(0)
	v_mfma_f32_16x16x32_bf16 v[130:133], v[146:149], v[200:203], v[130:133]
	v_mfma_f32_16x16x32_bf16 v[126:129], v[160:163], v[200:203], v[126:129]
	v_mfma_f32_16x16x32_bf16 v[114:117], v[146:149], v[208:211], v[114:117]
	v_mfma_f32_16x16x32_bf16 v[110:113], v[160:163], v[208:211], v[110:113]
	v_mfma_f32_16x16x32_bf16 v[98:101], v[146:149], v[216:219], v[98:101]
	v_mfma_f32_16x16x32_bf16 v[94:97], v[160:163], v[216:219], v[94:97]
	v_mfma_f32_16x16x32_bf16 v[78:81], v[146:149], v[224:227], v[78:81]
	v_mfma_f32_16x16x32_bf16 v[74:77], v[160:163], v[224:227], v[74:77]
	v_mfma_f32_16x16x32_bf16 v[130:133], v[150:153], v[204:207], v[130:133]
	v_mfma_f32_16x16x32_bf16 v[126:129], v[164:167], v[204:207], v[126:129]
	v_mfma_f32_16x16x32_bf16 v[114:117], v[150:153], v[212:215], v[114:117]
	v_mfma_f32_16x16x32_bf16 v[110:113], v[164:167], v[212:215], v[110:113]
	v_mfma_f32_16x16x32_bf16 v[98:101], v[150:153], v[220:223], v[98:101]
	v_mfma_f32_16x16x32_bf16 v[94:97], v[164:167], v[220:223], v[94:97]
	v_mfma_f32_16x16x32_bf16 v[78:81], v[150:153], v[228:231], v[78:81]
	v_mfma_f32_16x16x32_bf16 v[74:77], v[164:167], v[228:231], v[74:77]
	s_setprio 0
	s_setprio 1
	v_mfma_f32_16x16x32_bf16 v[122:125], v[168:171], v[200:203], v[122:125]
	v_mfma_f32_16x16x32_bf16 v[118:121], v[180:183], v[200:203], v[118:121]
	v_mfma_f32_16x16x32_bf16 v[106:109], v[168:171], v[208:211], v[106:109]
	v_mfma_f32_16x16x32_bf16 v[102:105], v[180:183], v[208:211], v[102:105]
	v_mfma_f32_16x16x32_bf16 v[90:93], v[168:171], v[216:219], v[90:93]
	v_mfma_f32_16x16x32_bf16 v[86:89], v[180:183], v[216:219], v[86:89]
	v_mfma_f32_16x16x32_bf16 v[70:73], v[168:171], v[224:227], v[70:73]
	v_mfma_f32_16x16x32_bf16 v[66:69], v[180:183], v[224:227], v[66:69]
	v_mfma_f32_16x16x32_bf16 v[122:125], v[172:175], v[204:207], v[122:125]
	v_mfma_f32_16x16x32_bf16 v[118:121], v[184:187], v[204:207], v[118:121]
	v_mfma_f32_16x16x32_bf16 v[106:109], v[172:175], v[212:215], v[106:109]
	v_mfma_f32_16x16x32_bf16 v[102:105], v[184:187], v[212:215], v[102:105]
	v_mfma_f32_16x16x32_bf16 v[90:93], v[172:175], v[220:223], v[90:93]
	v_mfma_f32_16x16x32_bf16 v[86:89], v[184:187], v[220:223], v[86:89]
	v_mfma_f32_16x16x32_bf16 v[70:73], v[172:175], v[228:231], v[70:73]
	v_mfma_f32_16x16x32_bf16 v[66:69], v[184:187], v[228:231], v[66:69]
	s_setprio 0
	s_barrier
	s_add_i32 s66, s66, s29
	v_lshl_add_u64 v[154:155], s[62:63], 0, v[138:139]
	s_mov_b32 m0, s66
	ds_read_b128 v[200:203], v158 offset:16384
	ds_read_b128 v[204:207], v158 offset:17408
	ds_read_b128 v[208:211], v158 offset:18432
	ds_read_b128 v[212:215], v158 offset:19456
	ds_read_b128 v[216:219], v158 offset:20480
	ds_read_b128 v[220:223], v158 offset:21504
	ds_read_b128 v[224:227], v158 offset:22528
	ds_read_b128 v[228:231], v158 offset:23552
	global_load_lds_dwordx4 v[154:155], off
	s_add_i32 m0, s66, 0x2000
	s_add_u32 s66, s62, 0x20000
	v_lshl_add_u64 v[176:177], s[62:63], 0, v[134:135]
	s_addc_u32 s67, s63, 0
	s_add_i32 s59, s59, s29
	global_load_lds_dwordx4 v[176:177], off
	v_lshl_add_u64 v[232:233], s[66:67], 0, v[138:139]
	s_mov_b32 m0, s59
	v_lshl_add_u64 v[234:235], s[64:65], 0, v[136:137]
	global_load_lds_dwordx4 v[232:233], off
	v_lshl_add_u64 v[232:233], s[66:67], 0, v[134:135]
	s_add_i32 m0, s59, 0x2000
	s_nop 0
	global_load_lds_dwordx4 v[232:233], off
	v_lshl_add_u64 v[232:233], s[64:65], 0, v[140:141]
	s_mov_b32 m0, s42
	s_nop 0
	global_load_lds_dwordx4 v[232:233], off
	s_mov_b32 m0, s48
	s_nop 0
	global_load_lds_dwordx4 v[234:235], off
	s_waitcnt vmcnt(8)
	s_waitcnt lgkmcnt(0)
	s_barrier
; #define PG8_STAGE(bufoff, gbase, voff) do { _Pragma("unroll") for (int _i = 0; _i < 2; ++_i) \
;         __builtin_amdgcn_global_load_lds((const unsigned*)((const char*)(gbase) + (voff)[_i]), (PG8_LAS unsigned*)(lds + (bufoff) + ldsw + _i * 8192), 16, 0, 0); } while (0)
; #define PG8_LDA(dst, b, h) do { _Pragma("unroll") for (int m = 0; m < 4; ++m) _Pragma("unroll") for (int k = 0; k < 2; ++k) dst[m][k] = *(const PG8_LAS bf16x8*)(lds + PG8_SA(b, h) + aoff + m * 2048 + k * 1024); } while (0)
; #define PG8_LDB(dst, b, h) do { _Pragma("unroll") for (int n = 0; n < 2; ++n) _Pragma("unroll") for (int k = 0; k < 2; ++k) dst[n][k] = *(const PG8_LAS bf16x8*)(lds + PG8_SB(b, h) + boff + n * 2048 + k * 1024); } while (0)
; #define PG8_MMA(ai, bj, At, Bt) do { __builtin_amdgcn_s_setprio(1); _Pragma("unroll") for (int m = 0; m < 4; ++m) _Pragma("unroll") for (int n = 0; n < 2; ++n) _Pragma("unroll") for (int k = 0; k < 2; ++k) \
;         acc[ai][bj][m][n] = __builtin_amdgcn_mfma_f32_16x16x32_bf16(Bt[n][k], At[m][k], acc[ai][bj][m][n], 0, 0, 0); __builtin_amdgcn_s_setprio(0); } while (0)
; #define PG8_WAIT_V(n) asm volatile("s_waitcnt vmcnt(" #n ")" ::: "memory")
; #define PG8_WAIT_L(n) asm volatile("s_waitcnt lgkmcnt(" #n ")" ::: "memory")
; #define PG8_BAR __builtin_amdgcn_s_barrier()
; #define PG8_SCHED __builtin_amdgcn_sched_barrier(0)
; template <class Epi, class Sched, bool ALIGN_EPI = false, bool SP2 = false>
; __device__ __forceinline__ void gemm_phase(PG8_LAS unsigned char* lds, const Gemm g, const Sched& S, const Epi& E) {
;     ...
;             PG8_WAIT_V(8); PG8_WAIT_L(0); PG8_BAR; PG8_MMA(1, 0, At, B0); PG8_MMA(1, 1, At, B1); PG8_BAR; PG8_SCHED;
;             PG8_LDB(B0, 1, 0); PG8_LDB(B1, 1, 1); PG8_SCHED; PG8_LDA(At, 1, 0); PG8_STAGE(PG8_SA(0, 1), a2 + hstep, voffA);
;             PG8_WAIT_V(8); PG8_WAIT_L(0); PG8_BAR; PG8_MMA(0, 0, At, B0); PG8_MMA(0, 1, At, B1); PG8_BAR; PG8_SCHED;
	s_setprio 1
	s_waitcnt lgkmcnt(0)
	v_mfma_f32_16x16x32_bf16 v[62:65], v[146:149], v[200:203], v[62:65]
	v_mfma_f32_16x16x32_bf16 v[58:61], v[160:163], v[200:203], v[58:61]
	v_mfma_f32_16x16x32_bf16 v[46:49], v[146:149], v[208:211], v[46:49]
	v_mfma_f32_16x16x32_bf16 v[42:45], v[160:163], v[208:211], v[42:45]
	v_mfma_f32_16x16x32_bf16 v[30:33], v[146:149], v[216:219], v[30:33]
	v_mfma_f32_16x16x32_bf16 v[26:29], v[160:163], v[216:219], v[26:29]
	v_mfma_f32_16x16x32_bf16 v[14:17], v[146:149], v[224:227], v[14:17]
	v_mfma_f32_16x16x32_bf16 v[10:13], v[160:163], v[224:227], v[10:13]
	v_mfma_f32_16x16x32_bf16 v[62:65], v[150:153], v[204:207], v[62:65]
	v_mfma_f32_16x16x32_bf16 v[58:61], v[164:167], v[204:207], v[58:61]
	v_mfma_f32_16x16x32_bf16 v[46:49], v[150:153], v[212:215], v[46:49]
	v_mfma_f32_16x16x32_bf16 v[42:45], v[164:167], v[212:215], v[42:45]
	v_mfma_f32_16x16x32_bf16 v[30:33], v[150:153], v[220:223], v[30:33]
	v_mfma_f32_16x16x32_bf16 v[26:29], v[164:167], v[220:223], v[26:29]
	v_mfma_f32_16x16x32_bf16 v[14:17], v[150:153], v[228:231], v[14:17]
	v_mfma_f32_16x16x32_bf16 v[10:13], v[164:167], v[228:231], v[10:13]
	s_setprio 0
	s_setprio 1
	v_mfma_f32_16x16x32_bf16 v[54:57], v[168:171], v[200:203], v[54:57]
	v_mfma_f32_16x16x32_bf16 v[50:53], v[180:183], v[200:203], v[50:53]
	v_mfma_f32_16x16x32_bf16 v[38:41], v[168:171], v[208:211], v[38:41]
	v_mfma_f32_16x16x32_bf16 v[34:37], v[180:183], v[208:211], v[34:37]
	v_mfma_f32_16x16x32_bf16 v[22:25], v[168:171], v[216:219], v[22:25]
	v_mfma_f32_16x16x32_bf16 v[18:21], v[180:183], v[216:219], v[18:21]
	v_mfma_f32_16x16x32_bf16 v[6:9], v[168:171], v[224:227], v[6:9]
	v_mfma_f32_16x16x32_bf16 v[2:5], v[180:183], v[224:227], v[2:5]
	v_mfma_f32_16x16x32_bf16 v[54:57], v[172:175], v[204:207], v[54:57]
	v_mfma_f32_16x16x32_bf16 v[50:53], v[184:187], v[204:207], v[50:53]
	v_mfma_f32_16x16x32_bf16 v[38:41], v[172:175], v[212:215], v[38:41]
	v_mfma_f32_16x16x32_bf16 v[34:37], v[184:187], v[212:215], v[34:37]
	v_mfma_f32_16x16x32_bf16 v[22:25], v[172:175], v[220:223], v[22:25]
	v_mfma_f32_16x16x32_bf16 v[18:21], v[184:187], v[220:223], v[18:21]
	v_mfma_f32_16x16x32_bf16 v[6:9], v[172:175], v[228:231], v[6:9]
	v_mfma_f32_16x16x32_bf16 v[2:5], v[184:187], v[228:231], v[2:5]
	s_setprio 0
	s_barrier
	s_add_i32 s59, 0, 0x18000
	v_add_u32_e32 v159, s59, v156
	s_add_i32 s66, 0, 0x1c000
	ds_read_b128 v[146:149], v159
	ds_read_b128 v[150:153], v159 offset:1024
	ds_read_b128 v[160:163], v159 offset:2048
	ds_read_b128 v[164:167], v159 offset:3072
	v_add_u32_e32 v159, s66, v156
	ds_read_b128 v[168:171], v159
	ds_read_b128 v[172:175], v159 offset:1024
	ds_read_b128 v[180:183], v159 offset:2048
	ds_read_b128 v[184:187], v159 offset:3072
	s_add_u32 s64, s64, 0x20000
	s_addc_u32 s65, s65, 0
	s_mov_b32 m0, s49
	v_lshl_add_u64 v[236:237], s[64:65], 0, v[140:141]
	ds_read_b128 v[200:203], v158 offset:32768
	ds_read_b128 v[204:207], v158 offset:33792
	ds_read_b128 v[208:211], v158 offset:34816
	ds_read_b128 v[212:215], v158 offset:35840
	ds_read_b128 v[216:219], v158 offset:36864
	ds_read_b128 v[220:223], v158 offset:37888
	ds_read_b128 v[224:227], v158 offset:38912
	ds_read_b128 v[228:231], v158 offset:39936
	global_load_lds_dwordx4 v[236:237], off
	v_lshl_add_u64 v[236:237], s[64:65], 0, v[136:137]
	s_mov_b32 m0, s52
	s_nop 0
	global_load_lds_dwordx4 v[236:237], off
	s_waitcnt vmcnt(8)
	s_waitcnt lgkmcnt(0)
	s_barrier
	s_setprio 1
	s_waitcnt lgkmcnt(0)
	v_mfma_f32_16x16x32_bf16 v[130:133], v[146:149], v[200:203], v[130:133]
	v_mfma_f32_16x16x32_bf16 v[126:129], v[160:163], v[200:203], v[126:129]
	v_mfma_f32_16x16x32_bf16 v[114:117], v[146:149], v[208:211], v[114:117]
	v_mfma_f32_16x16x32_bf16 v[110:113], v[160:163], v[208:211], v[110:113]
	v_mfma_f32_16x16x32_bf16 v[98:101], v[146:149], v[216:219], v[98:101]
	v_mfma_f32_16x16x32_bf16 v[94:97], v[160:163], v[216:219], v[94:97]
	v_mfma_f32_16x16x32_bf16 v[78:81], v[146:149], v[224:227], v[78:81]
	v_mfma_f32_16x16x32_bf16 v[74:77], v[160:163], v[224:227], v[74:77]
	v_mfma_f32_16x16x32_bf16 v[130:133], v[150:153], v[204:207], v[130:133]
	v_mfma_f32_16x16x32_bf16 v[126:129], v[164:167], v[204:207], v[126:129]
	v_mfma_f32_16x16x32_bf16 v[114:117], v[150:153], v[212:215], v[114:117]
	v_mfma_f32_16x16x32_bf16 v[110:113], v[164:167], v[212:215], v[110:113]
	v_mfma_f32_16x16x32_bf16 v[98:101], v[150:153], v[220:223], v[98:101]
	v_mfma_f32_16x16x32_bf16 v[94:97], v[164:167], v[220:223], v[94:97]
	v_mfma_f32_16x16x32_bf16 v[78:81], v[150:153], v[228:231], v[78:81]
	v_mfma_f32_16x16x32_bf16 v[74:77], v[164:167], v[228:231], v[74:77]
	s_setprio 0
	s_setprio 1
	v_mfma_f32_16x16x32_bf16 v[122:125], v[168:171], v[200:203], v[122:125]
	v_mfma_f32_16x16x32_bf16 v[118:121], v[180:183], v[200:203], v[118:121]
	v_mfma_f32_16x16x32_bf16 v[106:109], v[168:171], v[208:211], v[106:109]
	v_mfma_f32_16x16x32_bf16 v[102:105], v[180:183], v[208:211], v[102:105]
	v_mfma_f32_16x16x32_bf16 v[90:93], v[168:171], v[216:219], v[90:93]
	v_mfma_f32_16x16x32_bf16 v[86:89], v[180:183], v[216:219], v[86:89]
	v_mfma_f32_16x16x32_bf16 v[70:73], v[168:171], v[224:227], v[70:73]
	v_mfma_f32_16x16x32_bf16 v[66:69], v[180:183], v[224:227], v[66:69]
	v_mfma_f32_16x16x32_bf16 v[122:125], v[172:175], v[204:207], v[122:125]
	v_mfma_f32_16x16x32_bf16 v[118:121], v[184:187], v[204:207], v[118:121]
	v_mfma_f32_16x16x32_bf16 v[106:109], v[172:175], v[212:215], v[106:109]
	v_mfma_f32_16x16x32_bf16 v[102:105], v[184:187], v[212:215], v[102:105]
	v_mfma_f32_16x16x32_bf16 v[90:93], v[172:175], v[220:223], v[90:93]
	v_mfma_f32_16x16x32_bf16 v[86:89], v[184:187], v[220:223], v[86:89]
	v_mfma_f32_16x16x32_bf16 v[70:73], v[172:175], v[228:231], v[70:73]
	v_mfma_f32_16x16x32_bf16 v[66:69], v[184:187], v[228:231], v[66:69]
	s_setprio 0
	s_barrier
; #define PG8_STAGE(bufoff, gbase, voff) do { _Pragma("unroll") for (int _i = 0; _i < 2; ++_i) \
;         __builtin_amdgcn_global_load_lds((const unsigned*)((const char*)(gbase) + (voff)[_i]), (PG8_LAS unsigned*)(lds + (bufoff) + ldsw + _i * 8192), 16, 0, 0); } while (0)
; #define PG8_LDA(dst, b, h) do { _Pragma("unroll") for (int m = 0; m < 4; ++m) _Pragma("unroll") for (int k = 0; k < 2; ++k) dst[m][k] = *(const PG8_LAS bf16x8*)(lds + PG8_SA(b, h) + aoff + m * 2048 + k * 1024); } while (0)
; #define PG8_MMA(ai, bj, At, Bt) do { __builtin_amdgcn_s_setprio(1); _Pragma("unroll") for (int m = 0; m < 4; ++m) _Pragma("unroll") for (int n = 0; n < 2; ++n) _Pragma("unroll") for (int k = 0; k < 2; ++k) \
;         acc[ai][bj][m][n] = __builtin_amdgcn_mfma_f32_16x16x32_bf16(Bt[n][k], At[m][k], acc[ai][bj][m][n], 0, 0, 0); __builtin_amdgcn_s_setprio(0); } while (0)
; #define PG8_WAIT_V(n) asm volatile("s_waitcnt vmcnt(" #n ")" ::: "memory")
; #define PG8_WAIT_L(n) asm volatile("s_waitcnt lgkmcnt(" #n ")" ::: "memory")
; #define PG8_BAR __builtin_amdgcn_s_barrier()
; #define PG8_SCHED __builtin_amdgcn_sched_barrier(0)
; template <class Epi, class Sched, bool ALIGN_EPI = false, bool SP2 = false>
; __device__ __forceinline__ void gemm_phase(PG8_LAS unsigned char* lds, const Gemm g, const Sched& S, const Epi& E) {
;     ...
;         for (int t = 0; t < nt; t += 2) {
;             const bool last = (t == nt - 2);
;             const char* a1 = cA + (size_t)(t + 1) * kstep;
;             const char* a2 = last ? nA : cA + (size_t)(t + 2) * kstep; const char* b2 = last ? nB : cB + (size_t)(t + 2) * kstep;
;             const char* a3 = a2 + kstep; const char* b3 = b2 + kstep;
;     ...
;             PG8_LDA(At, 1, 1); PG8_STAGE(PG8_SB(1, 0), b3, voffB); PG8_STAGE(PG8_SB(1, 1), b3 + hstep, voffB); PG8_STAGE(PG8_SA(1, 0), a3, voffA);
;             PG8_WAIT_V(8); PG8_WAIT_L(0); PG8_BAR; PG8_MMA(1, 0, At, B0); PG8_MMA(1, 1, At, B1); PG8_BAR; PG8_SCHED;
	s_add_i32 s59, s59, s29
	v_lshl_add_u64 v[154:155], v[154:155], 0, s[38:39]
	s_mov_b32 m0, s59
	ds_read_b128 v[200:203], v158 offset:49152
	ds_read_b128 v[204:207], v158 offset:50176
	ds_read_b128 v[208:211], v158 offset:51200
	ds_read_b128 v[212:215], v158 offset:52224
	ds_read_b128 v[216:219], v158 offset:53248
	ds_read_b128 v[220:223], v158 offset:54272
	ds_read_b128 v[224:227], v158 offset:55296
	ds_read_b128 v[228:231], v158 offset:56320
	global_load_lds_dwordx4 v[154:155], off
	s_add_i32 m0, s59, 0x2000
	s_add_u32 s62, s62, 0x20080
	v_lshl_add_u64 v[154:155], v[176:177], 0, s[38:39]
	s_addc_u32 s63, s63, 0
	s_add_i32 s59, s66, s29
	global_load_lds_dwordx4 v[154:155], off
	v_lshl_add_u64 v[154:155], s[62:63], 0, v[138:139]
	s_mov_b32 m0, s59
	s_nop 0
	global_load_lds_dwordx4 v[154:155], off
	v_lshl_add_u64 v[154:155], s[62:63], 0, v[134:135]
	s_add_i32 m0, s59, 0x2000
	s_nop 0
	global_load_lds_dwordx4 v[154:155], off
	v_lshl_add_u64 v[154:155], v[232:233], 0, s[38:39]
	s_mov_b32 m0, s53
	s_nop 0
	global_load_lds_dwordx4 v[154:155], off
	v_lshl_add_u64 v[154:155], v[234:235], 0, s[38:39]
	s_mov_b32 m0, s54
	s_nop 0
	global_load_lds_dwordx4 v[154:155], off
	s_waitcnt vmcnt(8)
	s_waitcnt lgkmcnt(0)
	s_barrier
	s_setprio 1
	s_waitcnt lgkmcnt(0)
	v_mfma_f32_16x16x32_bf16 v[62:65], v[146:149], v[200:203], v[62:65]
	v_mfma_f32_16x16x32_bf16 v[58:61], v[160:163], v[200:203], v[58:61]
	v_mfma_f32_16x16x32_bf16 v[46:49], v[146:149], v[208:211], v[46:49]
	v_mfma_f32_16x16x32_bf16 v[42:45], v[160:163], v[208:211], v[42:45]
	v_mfma_f32_16x16x32_bf16 v[30:33], v[146:149], v[216:219], v[30:33]
	v_mfma_f32_16x16x32_bf16 v[26:29], v[160:163], v[216:219], v[26:29]
	v_mfma_f32_16x16x32_bf16 v[14:17], v[146:149], v[224:227], v[14:17]
	v_mfma_f32_16x16x32_bf16 v[10:13], v[160:163], v[224:227], v[10:13]
	v_mfma_f32_16x16x32_bf16 v[62:65], v[150:153], v[204:207], v[62:65]
	v_mfma_f32_16x16x32_bf16 v[58:61], v[164:167], v[204:207], v[58:61]
	v_mfma_f32_16x16x32_bf16 v[46:49], v[150:153], v[212:215], v[46:49]
	v_mfma_f32_16x16x32_bf16 v[42:45], v[164:167], v[212:215], v[42:45]
	v_mfma_f32_16x16x32_bf16 v[30:33], v[150:153], v[220:223], v[30:33]
	v_mfma_f32_16x16x32_bf16 v[26:29], v[164:167], v[220:223], v[26:29]
	v_mfma_f32_16x16x32_bf16 v[14:17], v[150:153], v[228:231], v[14:17]
	v_mfma_f32_16x16x32_bf16 v[10:13], v[164:167], v[228:231], v[10:13]
	s_setprio 0
	s_setprio 1
	v_mfma_f32_16x16x32_bf16 v[54:57], v[168:171], v[200:203], v[54:57]
	v_mfma_f32_16x16x32_bf16 v[50:53], v[180:183], v[200:203], v[50:53]
	v_mfma_f32_16x16x32_bf16 v[38:41], v[168:171], v[208:211], v[38:41]
	v_mfma_f32_16x16x32_bf16 v[34:37], v[180:183], v[208:211], v[34:37]
	v_mfma_f32_16x16x32_bf16 v[22:25], v[168:171], v[216:219], v[22:25]
	v_mfma_f32_16x16x32_bf16 v[18:21], v[180:183], v[216:219], v[18:21]
	v_mfma_f32_16x16x32_bf16 v[6:9], v[168:171], v[224:227], v[6:9]
	v_mfma_f32_16x16x32_bf16 v[2:5], v[180:183], v[224:227], v[2:5]
	v_mfma_f32_16x16x32_bf16 v[54:57], v[172:175], v[204:207], v[54:57]
	v_mfma_f32_16x16x32_bf16 v[50:53], v[184:187], v[204:207], v[50:53]
	v_mfma_f32_16x16x32_bf16 v[38:41], v[172:175], v[212:215], v[38:41]
	v_mfma_f32_16x16x32_bf16 v[34:37], v[184:187], v[212:215], v[34:37]
	v_mfma_f32_16x16x32_bf16 v[22:25], v[172:175], v[220:223], v[22:25]
	v_mfma_f32_16x16x32_bf16 v[18:21], v[184:187], v[220:223], v[18:21]
	v_mfma_f32_16x16x32_bf16 v[6:9], v[172:175], v[228:231], v[6:9]
	v_mfma_f32_16x16x32_bf16 v[2:5], v[184:187], v[228:231], v[2:5]
	s_setprio 0
	s_add_i32 s56, s56, 2
	s_add_u32 s40, s40, 0x100
	s_addc_u32 s41, s41, 0
	s_add_u32 s60, s60, 0x100
	s_addc_u32 s61, s61, 0
	s_cmp_gt_u32 s56, 5
	s_cbranch_scc1 .Lk_p3a2_exit
	s_add_u32 s59, s60, 0xfffe0080
	s_addc_u32 s62, s61, -1
	s_add_i32 s66, 0, 0x10000
	s_cmp_eq_u32 s56, 4
	s_cselect_b32 s65, s19, s62
	s_cselect_b32 s64, s23, s59
	v_add_u32_e32 v154, s66, v156
	s_cselect_b32 s63, s17, s41
	s_cselect_b32 s62, s27, s40
	s_add_i32 s59, 0, 0x14000
	s_branch .Lk_p3a2_head
.Lk_p3a2_exit:
	s_barrier
	s_and_b64 vcc, exec, s[14:15]
	s_cbranch_vccz .LBB0_703
	s_barrier

; template <class Epi, class Sched, bool ALIGN_EPI = false, bool SP2 = false>
; __device__ __forceinline__ void gemm_phase(PG8_LAS unsigned char* lds, const Gemm g, const Sched& S, const Epi& E) {
;     ...
;         for (int t = 0; t < nt; t += 2) {
;             const bool last = (t == nt - 2);
;             const char* a1 = cA + (size_t)(t + 1) * kstep;
;             const char* a2 = last ? nA : cA + (size_t)(t + 2) * kstep; const char* b2 = last ? nB : cB + (size_t)(t + 2) * kstep;
;             const char* a3 = a2 + kstep; const char* b3 = b2 + kstep;
.LBB0_770:
	s_add_u32 s65, s66, 0xfffc0080
	s_addc_u32 s68, s67, -1
	s_add_i32 s72, 0, 0x10000
	s_cmp_eq_u32 s63, 12
	s_cselect_b32 s71, s27, s68
	s_cselect_b32 s70, s53, s65
	v_add_u32_e32 v146, s72, v148
	s_cselect_b32 s69, s25, s56
	s_cselect_b32 s68, s54, s55
	s_add_i32 s65, 0, 0x14000
	s_branch .Lk_p3b_body

; #define PG8_STAGE(bufoff, gbase, voff) do { _Pragma("unroll") for (int _i = 0; _i < 2; ++_i) \
;         __builtin_amdgcn_global_load_lds((const unsigned*)((const char*)(gbase) + (voff)[_i]), (PG8_LAS unsigned*)(lds + (bufoff) + ldsw + _i * 8192), 16, 0, 0); } while (0)
; #define PG8_LDA(dst, b, h) do { _Pragma("unroll") for (int m = 0; m < 4; ++m) _Pragma("unroll") for (int k = 0; k < 2; ++k) dst[m][k] = *(const PG8_LAS bf16x8*)(lds + PG8_SA(b, h) + aoff + m * 2048 + k * 1024); } while (0)
; #define PG8_LDB(dst, b, h) do { _Pragma("unroll") for (int n = 0; n < 2; ++n) _Pragma("unroll") for (int k = 0; k < 2; ++k) dst[n][k] = *(const PG8_LAS bf16x8*)(lds + PG8_SB(b, h) + boff + n * 2048 + k * 1024); } while (0)
; #define PG8_MMA(ai, bj, At, Bt) do { __builtin_amdgcn_s_setprio(1); _Pragma("unroll") for (int m = 0; m < 4; ++m) _Pragma("unroll") for (int n = 0; n < 2; ++n) _Pragma("unroll") for (int k = 0; k < 2; ++k) \
;         acc[ai][bj][m][n] = __builtin_amdgcn_mfma_f32_16x16x32_bf16(Bt[n][k], At[m][k], acc[ai][bj][m][n], 0, 0, 0); __builtin_amdgcn_s_setprio(0); } while (0)
; #define PG8_WAIT_V(n) asm volatile("s_waitcnt vmcnt(" #n ")" ::: "memory")
; #define PG8_WAIT_L(n) asm volatile("s_waitcnt lgkmcnt(" #n ")" ::: "memory")
; #define PG8_BAR __builtin_amdgcn_s_barrier()
; #define PG8_SCHED __builtin_amdgcn_sched_barrier(0)
; template <class Epi, class Sched, bool ALIGN_EPI = false, bool SP2 = false>
; __device__ __forceinline__ void gemm_phase(PG8_LAS unsigned char* lds, const Gemm g, const Sched& S, const Epi& E) {
;     ...
;             PG8_LDB(B0, 0, 0); PG8_LDB(B1, 0, 1); PG8_SCHED; PG8_LDA(At, 0, 0); PG8_STAGE(PG8_SA(1, 1), a1 + hstep, voffA);
;             PG8_WAIT_V(8); PG8_WAIT_L(0); PG8_BAR; PG8_MMA(0, 0, At, B0); PG8_MMA(0, 1, At, B1); PG8_BAR; PG8_SCHED;
;             PG8_LDA(At, 0, 1); PG8_STAGE(PG8_SB(0, 0), b2, voffB); PG8_STAGE(PG8_SB(0, 1), b2 + hstep, voffB); PG8_STAGE(PG8_SA(0, 0), a2, voffA);
;             PG8_WAIT_V(8); PG8_WAIT_L(0); PG8_BAR; PG8_MMA(1, 0, At, B0); PG8_MMA(1, 1, At, B1); PG8_BAR; PG8_SCHED;
.Lk_p3b_body:
	ds_read_b128 v[142:145], v146
	ds_read_b128 v[152:155], v146 offset:1024
	ds_read_b128 v[156:159], v146 offset:2048
	ds_read_b128 v[160:163], v146 offset:3072
	v_add_u32_e32 v146, s65, v148
	ds_read_b128 v[164:167], v146
	ds_read_b128 v[168:171], v146 offset:1024
	ds_read_b128 v[172:175], v146 offset:2048
	ds_read_b128 v[180:183], v146 offset:3072
	v_lshl_add_u64 v[146:147], s[66:67], 0, v[140:141]
	s_add_i32 m0, s29, 0xc000
	ds_read_b128 v[184:187], v150
	ds_read_b128 v[200:203], v150 offset:1024
	ds_read_b128 v[204:207], v150 offset:2048
	ds_read_b128 v[208:211], v150 offset:3072
	ds_read_b128 v[212:215], v150 offset:4096
	ds_read_b128 v[216:219], v150 offset:5120
	ds_read_b128 v[220:223], v150 offset:6144
	ds_read_b128 v[224:227], v150 offset:7168
	global_load_lds_dwordx4 v[146:147], off
	v_lshl_add_u64 v[146:147], s[66:67], 0, v[138:139]
	s_add_i32 m0, s29, 0xe000
	s_nop 0
	global_load_lds_dwordx4 v[146:147], off
	s_waitcnt vmcnt(8)
	s_waitcnt lgkmcnt(0)
	s_barrier
	s_setprio 1
	s_waitcnt lgkmcnt(0)
	v_mfma_f32_16x16x32_bf16 v[130:133], v[142:145], v[184:187], v[130:133]
	v_mfma_f32_16x16x32_bf16 v[126:129], v[156:159], v[184:187], v[126:129]
	v_mfma_f32_16x16x32_bf16 v[114:117], v[142:145], v[204:207], v[114:117]
	v_mfma_f32_16x16x32_bf16 v[110:113], v[156:159], v[204:207], v[110:113]
	v_mfma_f32_16x16x32_bf16 v[98:101], v[142:145], v[212:215], v[98:101]
	v_mfma_f32_16x16x32_bf16 v[94:97], v[156:159], v[212:215], v[94:97]
	v_mfma_f32_16x16x32_bf16 v[78:81], v[142:145], v[220:223], v[78:81]
	v_mfma_f32_16x16x32_bf16 v[74:77], v[156:159], v[220:223], v[74:77]
	v_mfma_f32_16x16x32_bf16 v[130:133], v[152:155], v[200:203], v[130:133]
	v_mfma_f32_16x16x32_bf16 v[126:129], v[160:163], v[200:203], v[126:129]
	v_mfma_f32_16x16x32_bf16 v[114:117], v[152:155], v[208:211], v[114:117]
	v_mfma_f32_16x16x32_bf16 v[110:113], v[160:163], v[208:211], v[110:113]
	v_mfma_f32_16x16x32_bf16 v[98:101], v[152:155], v[216:219], v[98:101]
	v_mfma_f32_16x16x32_bf16 v[94:97], v[160:163], v[216:219], v[94:97]
	v_mfma_f32_16x16x32_bf16 v[78:81], v[152:155], v[224:227], v[78:81]
	v_mfma_f32_16x16x32_bf16 v[74:77], v[160:163], v[224:227], v[74:77]
	s_setprio 0
	s_setprio 1
	v_mfma_f32_16x16x32_bf16 v[122:125], v[164:167], v[184:187], v[122:125]
	v_mfma_f32_16x16x32_bf16 v[118:121], v[172:175], v[184:187], v[118:121]
	v_mfma_f32_16x16x32_bf16 v[106:109], v[164:167], v[204:207], v[106:109]
	v_mfma_f32_16x16x32_bf16 v[102:105], v[172:175], v[204:207], v[102:105]
	v_mfma_f32_16x16x32_bf16 v[90:93], v[164:167], v[212:215], v[90:93]
	v_mfma_f32_16x16x32_bf16 v[86:89], v[172:175], v[212:215], v[86:89]
	v_mfma_f32_16x16x32_bf16 v[70:73], v[164:167], v[220:223], v[70:73]
	v_mfma_f32_16x16x32_bf16 v[66:69], v[172:175], v[220:223], v[66:69]
	v_mfma_f32_16x16x32_bf16 v[122:125], v[168:171], v[200:203], v[122:125]
	v_mfma_f32_16x16x32_bf16 v[118:121], v[180:183], v[200:203], v[118:121]
	v_mfma_f32_16x16x32_bf16 v[106:109], v[168:171], v[208:211], v[106:109]
	v_mfma_f32_16x16x32_bf16 v[102:105], v[180:183], v[208:211], v[102:105]
	v_mfma_f32_16x16x32_bf16 v[90:93], v[168:171], v[216:219], v[90:93]
	v_mfma_f32_16x16x32_bf16 v[86:89], v[180:183], v[216:219], v[86:89]
	v_mfma_f32_16x16x32_bf16 v[70:73], v[168:171], v[224:227], v[70:73]
	v_mfma_f32_16x16x32_bf16 v[66:69], v[180:183], v[224:227], v[66:69]
	s_setprio 0
	s_barrier
	s_add_i32 s72, s72, s28
	v_lshl_add_u64 v[146:147], s[68:69], 0, v[134:135]
	s_mov_b32 m0, s72
	ds_read_b128 v[184:187], v150 offset:16384
	ds_read_b128 v[200:203], v150 offset:17408
	ds_read_b128 v[204:207], v150 offset:18432
	ds_read_b128 v[208:211], v150 offset:19456
	ds_read_b128 v[212:215], v150 offset:20480
	ds_read_b128 v[216:219], v150 offset:21504
	ds_read_b128 v[220:223], v150 offset:22528
	ds_read_b128 v[224:227], v150 offset:23552
	global_load_lds_dwordx4 v[146:147], off
	s_add_i32 m0, s72, 0x2000
	s_add_u32 s72, s68, 0x40000
	v_lshl_add_u64 v[176:177], s[68:69], 0, v[136:137]
	s_addc_u32 s73, s69, 0
	s_add_i32 s65, s65, s28
	global_load_lds_dwordx4 v[176:177], off
	v_lshl_add_u64 v[228:229], s[72:73], 0, v[134:135]
	s_mov_b32 m0, s65
	v_lshl_add_u64 v[230:231], s[70:71], 0, v[136:137]
	global_load_lds_dwordx4 v[228:229], off
	v_lshl_add_u64 v[228:229], s[72:73], 0, v[136:137]
	s_add_i32 m0, s65, 0x2000
	s_nop 0
	global_load_lds_dwordx4 v[228:229], off
	v_lshl_add_u64 v[228:229], s[70:71], 0, v[134:135]
	s_mov_b32 m0, s29
	s_nop 0
	global_load_lds_dwordx4 v[228:229], off
	s_mov_b32 m0, s34
	s_nop 0
	global_load_lds_dwordx4 v[230:231], off
	s_waitcnt vmcnt(8)
	s_waitcnt lgkmcnt(0)
	s_barrier
; #define PG8_STAGE(bufoff, gbase, voff) do { _Pragma("unroll") for (int _i = 0; _i < 2; ++_i) \
;         __builtin_amdgcn_global_load_lds((const unsigned*)((const char*)(gbase) + (voff)[_i]), (PG8_LAS unsigned*)(lds + (bufoff) + ldsw + _i * 8192), 16, 0, 0); } while (0)
; #define PG8_LDA(dst, b, h) do { _Pragma("unroll") for (int m = 0; m < 4; ++m) _Pragma("unroll") for (int k = 0; k < 2; ++k) dst[m][k] = *(const PG8_LAS bf16x8*)(lds + PG8_SA(b, h) + aoff + m * 2048 + k * 1024); } while (0)
; #define PG8_LDB(dst, b, h) do { _Pragma("unroll") for (int n = 0; n < 2; ++n) _Pragma("unroll") for (int k = 0; k < 2; ++k) dst[n][k] = *(const PG8_LAS bf16x8*)(lds + PG8_SB(b, h) + boff + n * 2048 + k * 1024); } while (0)
; #define PG8_MMA(ai, bj, At, Bt) do { __builtin_amdgcn_s_setprio(1); _Pragma("unroll") for (int m = 0; m < 4; ++m) _Pragma("unroll") for (int n = 0; n < 2; ++n) _Pragma("unroll") for (int k = 0; k < 2; ++k) \
;         acc[ai][bj][m][n] = __builtin_amdgcn_mfma_f32_16x16x32_bf16(Bt[n][k], At[m][k], acc[ai][bj][m][n], 0, 0, 0); __builtin_amdgcn_s_setprio(0); } while (0)
; #define PG8_WAIT_V(n) asm volatile("s_waitcnt vmcnt(" #n ")" ::: "memory")
; #define PG8_WAIT_L(n) asm volatile("s_waitcnt lgkmcnt(" #n ")" ::: "memory")
; #define PG8_BAR __builtin_amdgcn_s_barrier()
; #define PG8_SCHED __builtin_amdgcn_sched_barrier(0)
; template <class Epi, class Sched, bool ALIGN_EPI = false, bool SP2 = false>
; __device__ __forceinline__ void gemm_phase(PG8_LAS unsigned char* lds, const Gemm g, const Sched& S, const Epi& E) {
;     ...
;             PG8_WAIT_V(8); PG8_WAIT_L(0); PG8_BAR; PG8_MMA(1, 0, At, B0); PG8_MMA(1, 1, At, B1); PG8_BAR; PG8_SCHED;
;             PG8_LDB(B0, 1, 0); PG8_LDB(B1, 1, 1); PG8_SCHED; PG8_LDA(At, 1, 0); PG8_STAGE(PG8_SA(0, 1), a2 + hstep, voffA);
;             PG8_WAIT_V(8); PG8_WAIT_L(0); PG8_BAR; PG8_MMA(0, 0, At, B0); PG8_MMA(0, 1, At, B1); PG8_BAR; PG8_SCHED;
	s_setprio 1
	s_waitcnt lgkmcnt(0)
	v_mfma_f32_16x16x32_bf16 v[62:65], v[142:145], v[184:187], v[62:65]
	v_mfma_f32_16x16x32_bf16 v[58:61], v[156:159], v[184:187], v[58:61]
	v_mfma_f32_16x16x32_bf16 v[46:49], v[142:145], v[204:207], v[46:49]
	v_mfma_f32_16x16x32_bf16 v[42:45], v[156:159], v[204:207], v[42:45]
	v_mfma_f32_16x16x32_bf16 v[30:33], v[142:145], v[212:215], v[30:33]
	v_mfma_f32_16x16x32_bf16 v[26:29], v[156:159], v[212:215], v[26:29]
	v_mfma_f32_16x16x32_bf16 v[14:17], v[142:145], v[220:223], v[14:17]
	v_mfma_f32_16x16x32_bf16 v[10:13], v[156:159], v[220:223], v[10:13]
	v_mfma_f32_16x16x32_bf16 v[62:65], v[152:155], v[200:203], v[62:65]
	v_mfma_f32_16x16x32_bf16 v[58:61], v[160:163], v[200:203], v[58:61]
	v_mfma_f32_16x16x32_bf16 v[46:49], v[152:155], v[208:211], v[46:49]
	v_mfma_f32_16x16x32_bf16 v[42:45], v[160:163], v[208:211], v[42:45]
	v_mfma_f32_16x16x32_bf16 v[30:33], v[152:155], v[216:219], v[30:33]
	v_mfma_f32_16x16x32_bf16 v[26:29], v[160:163], v[216:219], v[26:29]
	v_mfma_f32_16x16x32_bf16 v[14:17], v[152:155], v[224:227], v[14:17]
	v_mfma_f32_16x16x32_bf16 v[10:13], v[160:163], v[224:227], v[10:13]
	s_setprio 0
	s_setprio 1
	v_mfma_f32_16x16x32_bf16 v[54:57], v[164:167], v[184:187], v[54:57]
	v_mfma_f32_16x16x32_bf16 v[50:53], v[172:175], v[184:187], v[50:53]
	v_mfma_f32_16x16x32_bf16 v[38:41], v[164:167], v[204:207], v[38:41]
	v_mfma_f32_16x16x32_bf16 v[34:37], v[172:175], v[204:207], v[34:37]
	v_mfma_f32_16x16x32_bf16 v[22:25], v[164:167], v[212:215], v[22:25]
	v_mfma_f32_16x16x32_bf16 v[18:21], v[172:175], v[212:215], v[18:21]
	v_mfma_f32_16x16x32_bf16 v[6:9], v[164:167], v[220:223], v[6:9]
	v_mfma_f32_16x16x32_bf16 v[2:5], v[172:175], v[220:223], v[2:5]
	v_mfma_f32_16x16x32_bf16 v[54:57], v[168:171], v[200:203], v[54:57]
	v_mfma_f32_16x16x32_bf16 v[50:53], v[180:183], v[200:203], v[50:53]
	v_mfma_f32_16x16x32_bf16 v[38:41], v[168:171], v[208:211], v[38:41]
	v_mfma_f32_16x16x32_bf16 v[34:37], v[180:183], v[208:211], v[34:37]
	v_mfma_f32_16x16x32_bf16 v[22:25], v[168:171], v[216:219], v[22:25]
	v_mfma_f32_16x16x32_bf16 v[18:21], v[180:183], v[216:219], v[18:21]
	v_mfma_f32_16x16x32_bf16 v[6:9], v[168:171], v[224:227], v[6:9]
	v_mfma_f32_16x16x32_bf16 v[2:5], v[180:183], v[224:227], v[2:5]
	s_setprio 0
	s_barrier
	s_add_i32 s65, 0, 0x18000
	v_add_u32_e32 v151, s65, v148
	s_add_i32 s72, 0, 0x1c000
	ds_read_b128 v[142:145], v151
	ds_read_b128 v[152:155], v151 offset:1024
	ds_read_b128 v[156:159], v151 offset:2048
	ds_read_b128 v[160:163], v151 offset:3072
	v_add_u32_e32 v151, s72, v148
	ds_read_b128 v[164:167], v151
	ds_read_b128 v[168:171], v151 offset:1024
	ds_read_b128 v[172:175], v151 offset:2048
	ds_read_b128 v[180:183], v151 offset:3072
	s_add_u32 s70, s70, 0x40000
	s_addc_u32 s71, s71, 0
	s_mov_b32 m0, s36
	v_lshl_add_u64 v[232:233], s[70:71], 0, v[134:135]
	ds_read_b128 v[184:187], v150 offset:32768
	ds_read_b128 v[200:203], v150 offset:33792
	ds_read_b128 v[204:207], v150 offset:34816
	ds_read_b128 v[208:211], v150 offset:35840
	ds_read_b128 v[212:215], v150 offset:36864
	ds_read_b128 v[216:219], v150 offset:37888
	ds_read_b128 v[220:223], v150 offset:38912
	ds_read_b128 v[224:227], v150 offset:39936
	global_load_lds_dwordx4 v[232:233], off
	v_lshl_add_u64 v[232:233], s[70:71], 0, v[136:137]
	s_mov_b32 m0, s37
	s_nop 0
	global_load_lds_dwordx4 v[232:233], off
	s_waitcnt vmcnt(8)
	s_waitcnt lgkmcnt(0)
	s_barrier
	s_setprio 1
	s_waitcnt lgkmcnt(0)
	v_mfma_f32_16x16x32_bf16 v[130:133], v[142:145], v[184:187], v[130:133]
	v_mfma_f32_16x16x32_bf16 v[126:129], v[156:159], v[184:187], v[126:129]
	v_mfma_f32_16x16x32_bf16 v[114:117], v[142:145], v[204:207], v[114:117]
	v_mfma_f32_16x16x32_bf16 v[110:113], v[156:159], v[204:207], v[110:113]
	v_mfma_f32_16x16x32_bf16 v[98:101], v[142:145], v[212:215], v[98:101]
	v_mfma_f32_16x16x32_bf16 v[94:97], v[156:159], v[212:215], v[94:97]
	v_mfma_f32_16x16x32_bf16 v[78:81], v[142:145], v[220:223], v[78:81]
	v_mfma_f32_16x16x32_bf16 v[74:77], v[156:159], v[220:223], v[74:77]
	v_mfma_f32_16x16x32_bf16 v[130:133], v[152:155], v[200:203], v[130:133]
	v_mfma_f32_16x16x32_bf16 v[126:129], v[160:163], v[200:203], v[126:129]
	v_mfma_f32_16x16x32_bf16 v[114:117], v[152:155], v[208:211], v[114:117]
	v_mfma_f32_16x16x32_bf16 v[110:113], v[160:163], v[208:211], v[110:113]
	v_mfma_f32_16x16x32_bf16 v[98:101], v[152:155], v[216:219], v[98:101]
	v_mfma_f32_16x16x32_bf16 v[94:97], v[160:163], v[216:219], v[94:97]
	v_mfma_f32_16x16x32_bf16 v[78:81], v[152:155], v[224:227], v[78:81]
	v_mfma_f32_16x16x32_bf16 v[74:77], v[160:163], v[224:227], v[74:77]
	s_setprio 0
	s_setprio 1
	v_mfma_f32_16x16x32_bf16 v[122:125], v[164:167], v[184:187], v[122:125]
	v_mfma_f32_16x16x32_bf16 v[118:121], v[172:175], v[184:187], v[118:121]
	v_mfma_f32_16x16x32_bf16 v[106:109], v[164:167], v[204:207], v[106:109]
	v_mfma_f32_16x16x32_bf16 v[102:105], v[172:175], v[204:207], v[102:105]
	v_mfma_f32_16x16x32_bf16 v[90:93], v[164:167], v[212:215], v[90:93]
	v_mfma_f32_16x16x32_bf16 v[86:89], v[172:175], v[212:215], v[86:89]
	v_mfma_f32_16x16x32_bf16 v[70:73], v[164:167], v[220:223], v[70:73]
	v_mfma_f32_16x16x32_bf16 v[66:69], v[172:175], v[220:223], v[66:69]
	v_mfma_f32_16x16x32_bf16 v[122:125], v[168:171], v[200:203], v[122:125]
	v_mfma_f32_16x16x32_bf16 v[118:121], v[180:183], v[200:203], v[118:121]
	v_mfma_f32_16x16x32_bf16 v[106:109], v[168:171], v[208:211], v[106:109]
	v_mfma_f32_16x16x32_bf16 v[102:105], v[180:183], v[208:211], v[102:105]
	v_mfma_f32_16x16x32_bf16 v[90:93], v[168:171], v[216:219], v[90:93]
	v_mfma_f32_16x16x32_bf16 v[86:89], v[180:183], v[216:219], v[86:89]
	v_mfma_f32_16x16x32_bf16 v[70:73], v[168:171], v[224:227], v[70:73]
	v_mfma_f32_16x16x32_bf16 v[66:69], v[180:183], v[224:227], v[66:69]
	s_setprio 0
	s_barrier
; #define PG8_STAGE(bufoff, gbase, voff) do { _Pragma("unroll") for (int _i = 0; _i < 2; ++_i) \
;         __builtin_amdgcn_global_load_lds((const unsigned*)((const char*)(gbase) + (voff)[_i]), (PG8_LAS unsigned*)(lds + (bufoff) + ldsw + _i * 8192), 16, 0, 0); } while (0)
; #define PG8_LDA(dst, b, h) do { _Pragma("unroll") for (int m = 0; m < 4; ++m) _Pragma("unroll") for (int k = 0; k < 2; ++k) dst[m][k] = *(const PG8_LAS bf16x8*)(lds + PG8_SA(b, h) + aoff + m * 2048 + k * 1024); } while (0)
; #define PG8_MMA(ai, bj, At, Bt) do { __builtin_amdgcn_s_setprio(1); _Pragma("unroll") for (int m = 0; m < 4; ++m) _Pragma("unroll") for (int n = 0; n < 2; ++n) _Pragma("unroll") for (int k = 0; k < 2; ++k) \
;         acc[ai][bj][m][n] = __builtin_amdgcn_mfma_f32_16x16x32_bf16(Bt[n][k], At[m][k], acc[ai][bj][m][n], 0, 0, 0); __builtin_amdgcn_s_setprio(0); } while (0)
; #define PG8_WAIT_V(n) asm volatile("s_waitcnt vmcnt(" #n ")" ::: "memory")
; #define PG8_WAIT_L(n) asm volatile("s_waitcnt lgkmcnt(" #n ")" ::: "memory")
; #define PG8_BAR __builtin_amdgcn_s_barrier()
; #define PG8_SCHED __builtin_amdgcn_sched_barrier(0)
; template <class Epi, class Sched, bool ALIGN_EPI = false, bool SP2 = false>
; __device__ __forceinline__ void gemm_phase(PG8_LAS unsigned char* lds, const Gemm g, const Sched& S, const Epi& E) {
;     ...
;         for (int t = 0; t < nt; t += 2) {
;             const bool last = (t == nt - 2);
;             const char* a1 = cA + (size_t)(t + 1) * kstep;
;             const char* a2 = last ? nA : cA + (size_t)(t + 2) * kstep; const char* b2 = last ? nB : cB + (size_t)(t + 2) * kstep;
;             const char* a3 = a2 + kstep; const char* b3 = b2 + kstep;
;     ...
;             PG8_LDA(At, 1, 1); PG8_STAGE(PG8_SB(1, 0), b3, voffB); PG8_STAGE(PG8_SB(1, 1), b3 + hstep, voffB); PG8_STAGE(PG8_SA(1, 0), a3, voffA);
;             PG8_WAIT_V(8); PG8_WAIT_L(0); PG8_BAR; PG8_MMA(1, 0, At, B0); PG8_MMA(1, 1, At, B1); PG8_BAR; PG8_SCHED;
	s_add_i32 s65, s65, s28
	v_lshl_add_u64 v[146:147], v[146:147], 0, s[38:39]
	s_mov_b32 m0, s65
	ds_read_b128 v[184:187], v150 offset:49152
	ds_read_b128 v[200:203], v150 offset:50176
	ds_read_b128 v[204:207], v150 offset:51200
	ds_read_b128 v[208:211], v150 offset:52224
	ds_read_b128 v[212:215], v150 offset:53248
	ds_read_b128 v[216:219], v150 offset:54272
	ds_read_b128 v[220:223], v150 offset:55296
	ds_read_b128 v[224:227], v150 offset:56320
	global_load_lds_dwordx4 v[146:147], off
	s_add_i32 m0, s65, 0x2000
	s_add_u32 s68, s68, 0x40080
	v_lshl_add_u64 v[146:147], v[176:177], 0, s[38:39]
	s_addc_u32 s69, s69, 0
	s_add_i32 s65, s72, s28
	global_load_lds_dwordx4 v[146:147], off
	v_lshl_add_u64 v[146:147], s[68:69], 0, v[134:135]
	s_mov_b32 m0, s65
	s_nop 0
	global_load_lds_dwordx4 v[146:147], off
	v_lshl_add_u64 v[146:147], s[68:69], 0, v[136:137]
	s_add_i32 m0, s65, 0x2000
	s_nop 0
	global_load_lds_dwordx4 v[146:147], off
	v_lshl_add_u64 v[146:147], v[228:229], 0, s[38:39]
	s_mov_b32 m0, s41
	s_nop 0
	global_load_lds_dwordx4 v[146:147], off
	v_lshl_add_u64 v[146:147], v[230:231], 0, s[38:39]
	s_mov_b32 m0, s42
	s_nop 0
	global_load_lds_dwordx4 v[146:147], off
	s_waitcnt vmcnt(8)
	s_waitcnt lgkmcnt(0)
	s_barrier
	s_setprio 1
	s_waitcnt lgkmcnt(0)
	v_mfma_f32_16x16x32_bf16 v[62:65], v[142:145], v[184:187], v[62:65]
	v_mfma_f32_16x16x32_bf16 v[58:61], v[156:159], v[184:187], v[58:61]
	v_mfma_f32_16x16x32_bf16 v[46:49], v[142:145], v[204:207], v[46:49]
	v_mfma_f32_16x16x32_bf16 v[42:45], v[156:159], v[204:207], v[42:45]
	v_mfma_f32_16x16x32_bf16 v[30:33], v[142:145], v[212:215], v[30:33]
	v_mfma_f32_16x16x32_bf16 v[26:29], v[156:159], v[212:215], v[26:29]
	v_mfma_f32_16x16x32_bf16 v[14:17], v[142:145], v[220:223], v[14:17]
	v_mfma_f32_16x16x32_bf16 v[10:13], v[156:159], v[220:223], v[10:13]
	v_mfma_f32_16x16x32_bf16 v[62:65], v[152:155], v[200:203], v[62:65]
	v_mfma_f32_16x16x32_bf16 v[58:61], v[160:163], v[200:203], v[58:61]
	v_mfma_f32_16x16x32_bf16 v[46:49], v[152:155], v[208:211], v[46:49]
	v_mfma_f32_16x16x32_bf16 v[42:45], v[160:163], v[208:211], v[42:45]
	v_mfma_f32_16x16x32_bf16 v[30:33], v[152:155], v[216:219], v[30:33]
	v_mfma_f32_16x16x32_bf16 v[26:29], v[160:163], v[216:219], v[26:29]
	v_mfma_f32_16x16x32_bf16 v[14:17], v[152:155], v[224:227], v[14:17]
	v_mfma_f32_16x16x32_bf16 v[10:13], v[160:163], v[224:227], v[10:13]
	s_setprio 0
	s_setprio 1
	v_mfma_f32_16x16x32_bf16 v[54:57], v[164:167], v[184:187], v[54:57]
	v_mfma_f32_16x16x32_bf16 v[50:53], v[172:175], v[184:187], v[50:53]
	v_mfma_f32_16x16x32_bf16 v[38:41], v[164:167], v[204:207], v[38:41]
	v_mfma_f32_16x16x32_bf16 v[34:37], v[172:175], v[204:207], v[34:37]
	v_mfma_f32_16x16x32_bf16 v[22:25], v[164:167], v[212:215], v[22:25]
	v_mfma_f32_16x16x32_bf16 v[18:21], v[172:175], v[212:215], v[18:21]
	v_mfma_f32_16x16x32_bf16 v[6:9], v[164:167], v[220:223], v[6:9]
	v_mfma_f32_16x16x32_bf16 v[2:5], v[172:175], v[220:223], v[2:5]
	v_mfma_f32_16x16x32_bf16 v[54:57], v[168:171], v[200:203], v[54:57]
	v_mfma_f32_16x16x32_bf16 v[50:53], v[180:183], v[200:203], v[50:53]
	v_mfma_f32_16x16x32_bf16 v[38:41], v[168:171], v[208:211], v[38:41]
	v_mfma_f32_16x16x32_bf16 v[34:37], v[180:183], v[208:211], v[34:37]
	v_mfma_f32_16x16x32_bf16 v[22:25], v[168:171], v[216:219], v[22:25]
	v_mfma_f32_16x16x32_bf16 v[18:21], v[180:183], v[216:219], v[18:21]
	v_mfma_f32_16x16x32_bf16 v[6:9], v[168:171], v[224:227], v[6:9]
	v_mfma_f32_16x16x32_bf16 v[2:5], v[180:183], v[224:227], v[2:5]
	s_setprio 0
	s_add_i32 s63, s63, 2
	s_add_u32 s55, s55, 0x100
	s_addc_u32 s56, s56, 0
	s_add_u32 s66, s66, 0x100
	s_addc_u32 s67, s67, 0
	s_cmp_gt_u32 s63, 13
	s_cbranch_scc1 .Lk_p3b_exit
	s_add_u32 s65, s66, 0xfffc0080
	s_addc_u32 s68, s67, -1
	s_add_i32 s72, 0, 0x10000
	s_cmp_eq_u32 s63, 12
	s_cselect_b32 s71, s27, s68
	s_cselect_b32 s70, s53, s65
	v_add_u32_e32 v146, s72, v148
	s_cselect_b32 s69, s25, s56
	s_cselect_b32 s68, s54, s55
	s_add_i32 s65, 0, 0x14000
	s_branch .Lk_p3b_head
.Lk_p3b_exit:
	s_barrier
	s_and_b64 vcc, exec, s[20:21]
	s_cbranch_vccz .LBB0_773
	s_barrier

; template <class Epi, class Sched, bool ALIGN_EPI = false, bool SP2 = false>
; __device__ __forceinline__ void gemm_phase(PG8_LAS unsigned char* lds, const Gemm g, const Sched& S, const Epi& E) {
;     ...
;         for (int t = 0; t < nt; t += 2) {
;             const bool last = (t == nt - 2);
;             const char* a1 = cA + (size_t)(t + 1) * kstep;
;             const char* a2 = last ? nA : cA + (size_t)(t + 2) * kstep; const char* b2 = last ? nB : cB + (size_t)(t + 2) * kstep;
;             const char* a3 = a2 + kstep; const char* b3 = b2 + kstep;
.LBB0_856:
	s_add_u32 s78, s76, 0xfffc0080
	s_addc_u32 s79, s77, -1
	s_add_i32 s84, 0, 0x10000
	s_cmp_eq_u32 s83, 12
	s_cselect_b32 s81, s56, s79
	s_cselect_b32 s80, s67, s78
	s_cselect_b32 s79, s65, s82
	s_cselect_b32 s78, s73, s75
	s_add_i32 s86, 0, 0x14000
	v_add_u32_e32 v146, s84, v177
	v_add_u32_e32 v174, s86, v177
	s_branch .Lk_p4_body

; #define PG8_STAGE(bufoff, gbase, voff) do { _Pragma("unroll") for (int _i = 0; _i < 2; ++_i) \
;         __builtin_amdgcn_global_load_lds((const unsigned*)((const char*)(gbase) + (voff)[_i]), (PG8_LAS unsigned*)(lds + (bufoff) + ldsw + _i * 8192), 16, 0, 0); } while (0)
; #define PG8_LDA(dst, b, h) do { _Pragma("unroll") for (int m = 0; m < 4; ++m) _Pragma("unroll") for (int k = 0; k < 2; ++k) dst[m][k] = *(const PG8_LAS bf16x8*)(lds + PG8_SA(b, h) + aoff + m * 2048 + k * 1024); } while (0)
; #define PG8_LDB(dst, b, h) do { _Pragma("unroll") for (int n = 0; n < 2; ++n) _Pragma("unroll") for (int k = 0; k < 2; ++k) dst[n][k] = *(const PG8_LAS bf16x8*)(lds + PG8_SB(b, h) + boff + n * 2048 + k * 1024); } while (0)
; #define PG8_MMA(ai, bj, At, Bt) do { __builtin_amdgcn_s_setprio(1); _Pragma("unroll") for (int m = 0; m < 4; ++m) _Pragma("unroll") for (int n = 0; n < 2; ++n) _Pragma("unroll") for (int k = 0; k < 2; ++k) \
;         acc[ai][bj][m][n] = __builtin_amdgcn_mfma_f32_16x16x32_bf16(Bt[n][k], At[m][k], acc[ai][bj][m][n], 0, 0, 0); __builtin_amdgcn_s_setprio(0); } while (0)
; #define PG8_WAIT_V(n) asm volatile("s_waitcnt vmcnt(" #n ")" ::: "memory")
; #define PG8_WAIT_L(n) asm volatile("s_waitcnt lgkmcnt(" #n ")" ::: "memory")
; #define PG8_BAR __builtin_amdgcn_s_barrier()
; #define PG8_SCHED __builtin_amdgcn_sched_barrier(0)
; template <class Epi, class Sched, bool ALIGN_EPI = false, bool SP2 = false>
; __device__ __forceinline__ void gemm_phase(PG8_LAS unsigned char* lds, const Gemm g, const Sched& S, const Epi& E) {
;     ...
;             PG8_LDB(B0, 0, 0); PG8_LDB(B1, 0, 1); PG8_SCHED; PG8_LDA(At, 0, 0); PG8_STAGE(PG8_SA(1, 1), a1 + hstep, voffA);
;             PG8_WAIT_V(8); PG8_WAIT_L(0); PG8_BAR; PG8_MMA(0, 0, At, B0); PG8_MMA(0, 1, At, B1); PG8_BAR; PG8_SCHED;
;             PG8_LDA(At, 0, 1); PG8_STAGE(PG8_SB(0, 0), b2, voffB); PG8_STAGE(PG8_SB(0, 1), b2 + hstep, voffB); PG8_STAGE(PG8_SA(0, 0), a2, voffA);
;             PG8_WAIT_V(8); PG8_WAIT_L(0); PG8_BAR; PG8_MMA(1, 0, At, B0); PG8_MMA(1, 1, At, B1); PG8_BAR; PG8_SCHED;
.Lk_p4_body:
	ds_read_b128 v[134:137], v146
	ds_read_b128 v[138:141], v146 offset:1024
	ds_read_b128 v[142:145], v146 offset:2048
	ds_read_b128 v[146:149], v146 offset:3072
	ds_read_b128 v[162:165], v174
	ds_read_b128 v[166:169], v174 offset:1024
	ds_read_b128 v[170:173], v174 offset:2048
	ds_read_b128 v[182:185], v174 offset:3072
	v_lshl_add_u64 v[174:175], s[76:77], 0, v[160:161]
	s_add_i32 m0, s36, 0xc000
	ds_read_b128 v[200:203], v180
	ds_read_b128 v[204:207], v180 offset:1024
	ds_read_b128 v[208:211], v180 offset:2048
	ds_read_b128 v[212:215], v180 offset:3072
	ds_read_b128 v[216:219], v180 offset:4096
	ds_read_b128 v[220:223], v180 offset:5120
	ds_read_b128 v[224:227], v180 offset:6144
	ds_read_b128 v[228:231], v180 offset:7168
	global_load_lds_dwordx4 v[174:175], off
	v_lshl_add_u64 v[174:175], s[76:77], 0, v[158:159]
	s_add_i32 m0, s36, 0xe000
	s_nop 0
	global_load_lds_dwordx4 v[174:175], off
	s_waitcnt vmcnt(8)
	s_waitcnt lgkmcnt(0)
	s_barrier
	s_setprio 1
	s_waitcnt lgkmcnt(0)
	v_mfma_f32_16x16x32_bf16 v[130:133], v[134:137], v[200:203], v[130:133]
	v_mfma_f32_16x16x32_bf16 v[102:105], v[142:145], v[200:203], v[102:105]
	v_mfma_f32_16x16x32_bf16 v[126:129], v[134:137], v[208:211], v[126:129]
	v_mfma_f32_16x16x32_bf16 v[98:101], v[142:145], v[208:211], v[98:101]
	v_mfma_f32_16x16x32_bf16 v[122:125], v[134:137], v[216:219], v[122:125]
	v_mfma_f32_16x16x32_bf16 v[90:93], v[142:145], v[216:219], v[90:93]
	v_mfma_f32_16x16x32_bf16 v[118:121], v[134:137], v[224:227], v[118:121]
	v_mfma_f32_16x16x32_bf16 v[86:89], v[142:145], v[224:227], v[86:89]
	v_mfma_f32_16x16x32_bf16 v[130:133], v[138:141], v[204:207], v[130:133]
	v_mfma_f32_16x16x32_bf16 v[102:105], v[146:149], v[204:207], v[102:105]
	v_mfma_f32_16x16x32_bf16 v[126:129], v[138:141], v[212:215], v[126:129]
	v_mfma_f32_16x16x32_bf16 v[98:101], v[146:149], v[212:215], v[98:101]
	v_mfma_f32_16x16x32_bf16 v[122:125], v[138:141], v[220:223], v[122:125]
	v_mfma_f32_16x16x32_bf16 v[90:93], v[146:149], v[220:223], v[90:93]
	v_mfma_f32_16x16x32_bf16 v[118:121], v[138:141], v[228:231], v[118:121]
	v_mfma_f32_16x16x32_bf16 v[86:89], v[146:149], v[228:231], v[86:89]
	s_setprio 0
	s_setprio 1
	v_mfma_f32_16x16x32_bf16 v[94:97], v[162:165], v[200:203], v[94:97]
	v_mfma_f32_16x16x32_bf16 v[66:69], v[170:173], v[200:203], v[66:69]
	v_mfma_f32_16x16x32_bf16 v[114:117], v[162:165], v[208:211], v[114:117]
	v_mfma_f32_16x16x32_bf16 v[78:81], v[170:173], v[208:211], v[78:81]
	v_mfma_f32_16x16x32_bf16 v[110:113], v[162:165], v[216:219], v[110:113]
	v_mfma_f32_16x16x32_bf16 v[74:77], v[170:173], v[216:219], v[74:77]
	v_mfma_f32_16x16x32_bf16 v[106:109], v[162:165], v[224:227], v[106:109]
	v_mfma_f32_16x16x32_bf16 v[70:73], v[170:173], v[224:227], v[70:73]
	v_mfma_f32_16x16x32_bf16 v[94:97], v[166:169], v[204:207], v[94:97]
	v_mfma_f32_16x16x32_bf16 v[66:69], v[182:185], v[204:207], v[66:69]
	v_mfma_f32_16x16x32_bf16 v[114:117], v[166:169], v[212:215], v[114:117]
	v_mfma_f32_16x16x32_bf16 v[78:81], v[182:185], v[212:215], v[78:81]
	v_mfma_f32_16x16x32_bf16 v[110:113], v[166:169], v[220:223], v[110:113]
	v_mfma_f32_16x16x32_bf16 v[74:77], v[182:185], v[220:223], v[74:77]
	v_mfma_f32_16x16x32_bf16 v[106:109], v[166:169], v[228:231], v[106:109]
	v_mfma_f32_16x16x32_bf16 v[70:73], v[182:185], v[228:231], v[70:73]
	s_setprio 0
	s_barrier
	s_add_i32 s84, s84, s34
	v_lshl_add_u64 v[174:175], s[78:79], 0, v[152:153]
	s_mov_b32 m0, s84
	ds_read_b128 v[200:203], v180 offset:16384
	ds_read_b128 v[204:207], v180 offset:17408
	ds_read_b128 v[208:211], v180 offset:18432
	ds_read_b128 v[212:215], v180 offset:19456
	ds_read_b128 v[216:219], v180 offset:20480
	ds_read_b128 v[220:223], v180 offset:21504
	ds_read_b128 v[224:227], v180 offset:22528
	ds_read_b128 v[228:231], v180 offset:23552
	global_load_lds_dwordx4 v[174:175], off
	s_add_i32 m0, s84, 0x2000
	s_add_u32 s84, s78, 0x40000
	v_lshl_add_u64 v[186:187], s[78:79], 0, v[156:157]
	s_addc_u32 s85, s79, 0
	s_add_i32 s86, s86, s34
	global_load_lds_dwordx4 v[186:187], off
	v_lshl_add_u64 v[232:233], s[84:85], 0, v[152:153]
	s_mov_b32 m0, s86
	v_lshl_add_u64 v[234:235], s[80:81], 0, v[154:155]
	global_load_lds_dwordx4 v[232:233], off
	v_lshl_add_u64 v[232:233], s[84:85], 0, v[156:157]
	s_add_i32 m0, s86, 0x2000
	s_nop 0
	global_load_lds_dwordx4 v[232:233], off
	v_lshl_add_u64 v[232:233], s[80:81], 0, v[150:151]
	s_mov_b32 m0, s36
	s_nop 0
	global_load_lds_dwordx4 v[232:233], off
	s_mov_b32 m0, s37
	s_nop 0
	global_load_lds_dwordx4 v[234:235], off
	s_waitcnt vmcnt(8)
	s_waitcnt lgkmcnt(0)
	s_barrier
; #define PG8_STAGE(bufoff, gbase, voff) do { _Pragma("unroll") for (int _i = 0; _i < 2; ++_i) \
;         __builtin_amdgcn_global_load_lds((const unsigned*)((const char*)(gbase) + (voff)[_i]), (PG8_LAS unsigned*)(lds + (bufoff) + ldsw + _i * 8192), 16, 0, 0); } while (0)
; #define PG8_LDA(dst, b, h) do { _Pragma("unroll") for (int m = 0; m < 4; ++m) _Pragma("unroll") for (int k = 0; k < 2; ++k) dst[m][k] = *(const PG8_LAS bf16x8*)(lds + PG8_SA(b, h) + aoff + m * 2048 + k * 1024); } while (0)
; #define PG8_LDB(dst, b, h) do { _Pragma("unroll") for (int n = 0; n < 2; ++n) _Pragma("unroll") for (int k = 0; k < 2; ++k) dst[n][k] = *(const PG8_LAS bf16x8*)(lds + PG8_SB(b, h) + boff + n * 2048 + k * 1024); } while (0)
; #define PG8_MMA(ai, bj, At, Bt) do { __builtin_amdgcn_s_setprio(1); _Pragma("unroll") for (int m = 0; m < 4; ++m) _Pragma("unroll") for (int n = 0; n < 2; ++n) _Pragma("unroll") for (int k = 0; k < 2; ++k) \
;         acc[ai][bj][m][n] = __builtin_amdgcn_mfma_f32_16x16x32_bf16(Bt[n][k], At[m][k], acc[ai][bj][m][n], 0, 0, 0); __builtin_amdgcn_s_setprio(0); } while (0)
; #define PG8_WAIT_V(n) asm volatile("s_waitcnt vmcnt(" #n ")" ::: "memory")
; #define PG8_WAIT_L(n) asm volatile("s_waitcnt lgkmcnt(" #n ")" ::: "memory")
; #define PG8_BAR __builtin_amdgcn_s_barrier()
; #define PG8_SCHED __builtin_amdgcn_sched_barrier(0)
; template <class Epi, class Sched, bool ALIGN_EPI = false, bool SP2 = false>
; __device__ __forceinline__ void gemm_phase(PG8_LAS unsigned char* lds, const Gemm g, const Sched& S, const Epi& E) {
;     ...
;             PG8_WAIT_V(8); PG8_WAIT_L(0); PG8_BAR; PG8_MMA(1, 0, At, B0); PG8_MMA(1, 1, At, B1); PG8_BAR; PG8_SCHED;
;             PG8_LDB(B0, 1, 0); PG8_LDB(B1, 1, 1); PG8_SCHED; PG8_LDA(At, 1, 0); PG8_STAGE(PG8_SA(0, 1), a2 + hstep, voffA);
;             PG8_WAIT_V(8); PG8_WAIT_L(0); PG8_BAR; PG8_MMA(0, 0, At, B0); PG8_MMA(0, 1, At, B1); PG8_BAR; PG8_SCHED;
	s_setprio 1
	s_waitcnt lgkmcnt(0)
	v_mfma_f32_16x16x32_bf16 v[62:65], v[134:137], v[200:203], v[62:65]
	v_mfma_f32_16x16x32_bf16 v[30:33], v[142:145], v[200:203], v[30:33]
	v_mfma_f32_16x16x32_bf16 v[58:61], v[134:137], v[208:211], v[58:61]
	v_mfma_f32_16x16x32_bf16 v[26:29], v[142:145], v[208:211], v[26:29]
	v_mfma_f32_16x16x32_bf16 v[54:57], v[134:137], v[216:219], v[54:57]
	v_mfma_f32_16x16x32_bf16 v[22:25], v[142:145], v[216:219], v[22:25]
	v_mfma_f32_16x16x32_bf16 v[50:53], v[134:137], v[224:227], v[50:53]
	v_mfma_f32_16x16x32_bf16 v[18:21], v[142:145], v[224:227], v[18:21]
	v_mfma_f32_16x16x32_bf16 v[62:65], v[138:141], v[204:207], v[62:65]
	v_mfma_f32_16x16x32_bf16 v[30:33], v[146:149], v[204:207], v[30:33]
	v_mfma_f32_16x16x32_bf16 v[58:61], v[138:141], v[212:215], v[58:61]
	v_mfma_f32_16x16x32_bf16 v[26:29], v[146:149], v[212:215], v[26:29]
	v_mfma_f32_16x16x32_bf16 v[54:57], v[138:141], v[220:223], v[54:57]
	v_mfma_f32_16x16x32_bf16 v[22:25], v[146:149], v[220:223], v[22:25]
	v_mfma_f32_16x16x32_bf16 v[50:53], v[138:141], v[228:231], v[50:53]
	v_mfma_f32_16x16x32_bf16 v[18:21], v[146:149], v[228:231], v[18:21]
	s_setprio 0
	s_setprio 1
	v_mfma_f32_16x16x32_bf16 v[34:37], v[162:165], v[200:203], v[34:37]
	v_mfma_f32_16x16x32_bf16 v[2:5], v[170:173], v[200:203], v[2:5]
	v_mfma_f32_16x16x32_bf16 v[46:49], v[162:165], v[208:211], v[46:49]
	v_mfma_f32_16x16x32_bf16 v[14:17], v[170:173], v[208:211], v[14:17]
	v_mfma_f32_16x16x32_bf16 v[42:45], v[162:165], v[216:219], v[42:45]
	v_mfma_f32_16x16x32_bf16 v[10:13], v[170:173], v[216:219], v[10:13]
	v_mfma_f32_16x16x32_bf16 v[38:41], v[162:165], v[224:227], v[38:41]
	v_mfma_f32_16x16x32_bf16 v[6:9], v[170:173], v[224:227], v[6:9]
	v_mfma_f32_16x16x32_bf16 v[34:37], v[166:169], v[204:207], v[34:37]
	v_mfma_f32_16x16x32_bf16 v[2:5], v[182:185], v[204:207], v[2:5]
	v_mfma_f32_16x16x32_bf16 v[46:49], v[166:169], v[212:215], v[46:49]
	v_mfma_f32_16x16x32_bf16 v[14:17], v[182:185], v[212:215], v[14:17]
	v_mfma_f32_16x16x32_bf16 v[42:45], v[166:169], v[220:223], v[42:45]
	v_mfma_f32_16x16x32_bf16 v[10:13], v[182:185], v[220:223], v[10:13]
	v_mfma_f32_16x16x32_bf16 v[38:41], v[166:169], v[228:231], v[38:41]
	v_mfma_f32_16x16x32_bf16 v[6:9], v[182:185], v[228:231], v[6:9]
	s_setprio 0
	s_barrier
	s_add_i32 s84, 0, 0x18000
	s_add_i32 s85, 0, 0x1c000
	v_add_u32_e32 v146, s84, v177
	v_add_u32_e32 v181, s85, v177
	ds_read_b128 v[134:137], v146
	ds_read_b128 v[138:141], v146 offset:1024
	ds_read_b128 v[142:145], v146 offset:2048
	ds_read_b128 v[146:149], v146 offset:3072
	ds_read_b128 v[162:165], v181
	ds_read_b128 v[166:169], v181 offset:1024
	ds_read_b128 v[170:173], v181 offset:2048
	ds_read_b128 v[182:185], v181 offset:3072
	s_add_u32 s80, s80, 0x40000
	s_addc_u32 s81, s81, 0
	s_mov_b32 m0, s40
	v_lshl_add_u64 v[236:237], s[80:81], 0, v[150:151]
	ds_read_b128 v[200:203], v180 offset:32768
	ds_read_b128 v[204:207], v180 offset:33792
	ds_read_b128 v[208:211], v180 offset:34816
	ds_read_b128 v[212:215], v180 offset:35840
	ds_read_b128 v[216:219], v180 offset:36864
	ds_read_b128 v[220:223], v180 offset:37888
	ds_read_b128 v[224:227], v180 offset:38912
	ds_read_b128 v[228:231], v180 offset:39936
	global_load_lds_dwordx4 v[236:237], off
	v_lshl_add_u64 v[236:237], s[80:81], 0, v[154:155]
	s_mov_b32 m0, s41
	s_nop 0
	global_load_lds_dwordx4 v[236:237], off
	s_waitcnt vmcnt(8)
	s_waitcnt lgkmcnt(0)
	s_barrier
	s_setprio 1
	s_waitcnt lgkmcnt(0)
	v_mfma_f32_16x16x32_bf16 v[130:133], v[134:137], v[200:203], v[130:133]
	v_mfma_f32_16x16x32_bf16 v[102:105], v[142:145], v[200:203], v[102:105]
	v_mfma_f32_16x16x32_bf16 v[126:129], v[134:137], v[208:211], v[126:129]
	v_mfma_f32_16x16x32_bf16 v[98:101], v[142:145], v[208:211], v[98:101]
	v_mfma_f32_16x16x32_bf16 v[122:125], v[134:137], v[216:219], v[122:125]
	v_mfma_f32_16x16x32_bf16 v[90:93], v[142:145], v[216:219], v[90:93]
	v_mfma_f32_16x16x32_bf16 v[118:121], v[134:137], v[224:227], v[118:121]
	v_mfma_f32_16x16x32_bf16 v[86:89], v[142:145], v[224:227], v[86:89]
	v_mfma_f32_16x16x32_bf16 v[130:133], v[138:141], v[204:207], v[130:133]
	v_mfma_f32_16x16x32_bf16 v[102:105], v[146:149], v[204:207], v[102:105]
	v_mfma_f32_16x16x32_bf16 v[126:129], v[138:141], v[212:215], v[126:129]
	v_mfma_f32_16x16x32_bf16 v[98:101], v[146:149], v[212:215], v[98:101]
	v_mfma_f32_16x16x32_bf16 v[122:125], v[138:141], v[220:223], v[122:125]
	v_mfma_f32_16x16x32_bf16 v[90:93], v[146:149], v[220:223], v[90:93]
	v_mfma_f32_16x16x32_bf16 v[118:121], v[138:141], v[228:231], v[118:121]
	v_mfma_f32_16x16x32_bf16 v[86:89], v[146:149], v[228:231], v[86:89]
	s_setprio 0
	s_setprio 1
	v_mfma_f32_16x16x32_bf16 v[94:97], v[162:165], v[200:203], v[94:97]
	v_mfma_f32_16x16x32_bf16 v[66:69], v[170:173], v[200:203], v[66:69]
	v_mfma_f32_16x16x32_bf16 v[114:117], v[162:165], v[208:211], v[114:117]
	v_mfma_f32_16x16x32_bf16 v[78:81], v[170:173], v[208:211], v[78:81]
	v_mfma_f32_16x16x32_bf16 v[110:113], v[162:165], v[216:219], v[110:113]
	v_mfma_f32_16x16x32_bf16 v[74:77], v[170:173], v[216:219], v[74:77]
	v_mfma_f32_16x16x32_bf16 v[106:109], v[162:165], v[224:227], v[106:109]
	v_mfma_f32_16x16x32_bf16 v[70:73], v[170:173], v[224:227], v[70:73]
	v_mfma_f32_16x16x32_bf16 v[94:97], v[166:169], v[204:207], v[94:97]
	v_mfma_f32_16x16x32_bf16 v[66:69], v[182:185], v[204:207], v[66:69]
	v_mfma_f32_16x16x32_bf16 v[114:117], v[166:169], v[212:215], v[114:117]
	v_mfma_f32_16x16x32_bf16 v[78:81], v[182:185], v[212:215], v[78:81]
	v_mfma_f32_16x16x32_bf16 v[110:113], v[166:169], v[220:223], v[110:113]
	v_mfma_f32_16x16x32_bf16 v[74:77], v[182:185], v[220:223], v[74:77]
	v_mfma_f32_16x16x32_bf16 v[106:109], v[166:169], v[228:231], v[106:109]
	v_mfma_f32_16x16x32_bf16 v[70:73], v[182:185], v[228:231], v[70:73]
	s_setprio 0
	s_barrier
; #define PG8_STAGE(bufoff, gbase, voff) do { _Pragma("unroll") for (int _i = 0; _i < 2; ++_i) \
;         __builtin_amdgcn_global_load_lds((const unsigned*)((const char*)(gbase) + (voff)[_i]), (PG8_LAS unsigned*)(lds + (bufoff) + ldsw + _i * 8192), 16, 0, 0); } while (0)
; #define PG8_LDA(dst, b, h) do { _Pragma("unroll") for (int m = 0; m < 4; ++m) _Pragma("unroll") for (int k = 0; k < 2; ++k) dst[m][k] = *(const PG8_LAS bf16x8*)(lds + PG8_SA(b, h) + aoff + m * 2048 + k * 1024); } while (0)
; #define PG8_MMA(ai, bj, At, Bt) do { __builtin_amdgcn_s_setprio(1); _Pragma("unroll") for (int m = 0; m < 4; ++m) _Pragma("unroll") for (int n = 0; n < 2; ++n) _Pragma("unroll") for (int k = 0; k < 2; ++k) \
;         acc[ai][bj][m][n] = __builtin_amdgcn_mfma_f32_16x16x32_bf16(Bt[n][k], At[m][k], acc[ai][bj][m][n], 0, 0, 0); __builtin_amdgcn_s_setprio(0); } while (0)
; #define PG8_WAIT_V(n) asm volatile("s_waitcnt vmcnt(" #n ")" ::: "memory")
; #define PG8_WAIT_L(n) asm volatile("s_waitcnt lgkmcnt(" #n ")" ::: "memory")
; #define PG8_BAR __builtin_amdgcn_s_barrier()
; #define PG8_SCHED __builtin_amdgcn_sched_barrier(0)
; template <class Epi, class Sched, bool ALIGN_EPI = false, bool SP2 = false>
; __device__ __forceinline__ void gemm_phase(PG8_LAS unsigned char* lds, const Gemm g, const Sched& S, const Epi& E) {
;     ...
;         for (int t = 0; t < nt; t += 2) {
;             const bool last = (t == nt - 2);
;             const char* a1 = cA + (size_t)(t + 1) * kstep;
;             const char* a2 = last ? nA : cA + (size_t)(t + 2) * kstep; const char* b2 = last ? nB : cB + (size_t)(t + 2) * kstep;
;             const char* a3 = a2 + kstep; const char* b3 = b2 + kstep;
;     ...
;             PG8_LDA(At, 1, 1); PG8_STAGE(PG8_SB(1, 0), b3, voffB); PG8_STAGE(PG8_SB(1, 1), b3 + hstep, voffB); PG8_STAGE(PG8_SA(1, 0), a3, voffA);
;             PG8_WAIT_V(8); PG8_WAIT_L(0); PG8_BAR; PG8_MMA(1, 0, At, B0); PG8_MMA(1, 1, At, B1); PG8_BAR; PG8_SCHED;
	s_add_i32 s80, s84, s34
	v_lshl_add_u64 v[174:175], v[174:175], 0, s[38:39]
	s_mov_b32 m0, s80
	ds_read_b128 v[200:203], v180 offset:49152
	ds_read_b128 v[204:207], v180 offset:50176
	ds_read_b128 v[208:211], v180 offset:51200
	ds_read_b128 v[212:215], v180 offset:52224
	ds_read_b128 v[216:219], v180 offset:53248
	ds_read_b128 v[220:223], v180 offset:54272
	ds_read_b128 v[224:227], v180 offset:55296
	ds_read_b128 v[228:231], v180 offset:56320
	global_load_lds_dwordx4 v[174:175], off
	s_add_i32 m0, s80, 0x2000
	s_add_u32 s78, s78, 0x40080
	v_lshl_add_u64 v[174:175], v[186:187], 0, s[38:39]
	s_addc_u32 s79, s79, 0
	s_add_i32 s80, s85, s34
	global_load_lds_dwordx4 v[174:175], off
	v_lshl_add_u64 v[174:175], s[78:79], 0, v[152:153]
	s_mov_b32 m0, s80
	s_nop 0
	global_load_lds_dwordx4 v[174:175], off
	v_lshl_add_u64 v[174:175], s[78:79], 0, v[156:157]
	s_add_i32 m0, s80, 0x2000
	s_nop 0
	global_load_lds_dwordx4 v[174:175], off
	v_lshl_add_u64 v[174:175], v[232:233], 0, s[38:39]
	s_mov_b32 m0, s52
	s_nop 0
	global_load_lds_dwordx4 v[174:175], off
	v_lshl_add_u64 v[174:175], v[234:235], 0, s[38:39]
	s_mov_b32 m0, s53
	s_nop 0
	global_load_lds_dwordx4 v[174:175], off
	s_waitcnt vmcnt(8)
	s_waitcnt lgkmcnt(0)
	s_barrier
	s_setprio 1
	s_waitcnt lgkmcnt(0)
	v_mfma_f32_16x16x32_bf16 v[62:65], v[134:137], v[200:203], v[62:65]
	v_mfma_f32_16x16x32_bf16 v[30:33], v[142:145], v[200:203], v[30:33]
	v_mfma_f32_16x16x32_bf16 v[58:61], v[134:137], v[208:211], v[58:61]
	v_mfma_f32_16x16x32_bf16 v[26:29], v[142:145], v[208:211], v[26:29]
	v_mfma_f32_16x16x32_bf16 v[54:57], v[134:137], v[216:219], v[54:57]
	v_mfma_f32_16x16x32_bf16 v[22:25], v[142:145], v[216:219], v[22:25]
	v_mfma_f32_16x16x32_bf16 v[50:53], v[134:137], v[224:227], v[50:53]
	v_mfma_f32_16x16x32_bf16 v[18:21], v[142:145], v[224:227], v[18:21]
	v_mfma_f32_16x16x32_bf16 v[62:65], v[138:141], v[204:207], v[62:65]
	v_mfma_f32_16x16x32_bf16 v[30:33], v[146:149], v[204:207], v[30:33]
	v_mfma_f32_16x16x32_bf16 v[58:61], v[138:141], v[212:215], v[58:61]
	v_mfma_f32_16x16x32_bf16 v[26:29], v[146:149], v[212:215], v[26:29]
	v_mfma_f32_16x16x32_bf16 v[54:57], v[138:141], v[220:223], v[54:57]
	v_mfma_f32_16x16x32_bf16 v[22:25], v[146:149], v[220:223], v[22:25]
	v_mfma_f32_16x16x32_bf16 v[50:53], v[138:141], v[228:231], v[50:53]
	v_mfma_f32_16x16x32_bf16 v[18:21], v[146:149], v[228:231], v[18:21]
	s_setprio 0
	s_setprio 1
	v_mfma_f32_16x16x32_bf16 v[34:37], v[162:165], v[200:203], v[34:37]
	v_mfma_f32_16x16x32_bf16 v[2:5], v[170:173], v[200:203], v[2:5]
	v_mfma_f32_16x16x32_bf16 v[46:49], v[162:165], v[208:211], v[46:49]
	v_mfma_f32_16x16x32_bf16 v[14:17], v[170:173], v[208:211], v[14:17]
	v_mfma_f32_16x16x32_bf16 v[42:45], v[162:165], v[216:219], v[42:45]
	v_mfma_f32_16x16x32_bf16 v[10:13], v[170:173], v[216:219], v[10:13]
	v_mfma_f32_16x16x32_bf16 v[38:41], v[162:165], v[224:227], v[38:41]
	v_mfma_f32_16x16x32_bf16 v[6:9], v[170:173], v[224:227], v[6:9]
	v_mfma_f32_16x16x32_bf16 v[34:37], v[166:169], v[204:207], v[34:37]
	v_mfma_f32_16x16x32_bf16 v[2:5], v[182:185], v[204:207], v[2:5]
	v_mfma_f32_16x16x32_bf16 v[46:49], v[166:169], v[212:215], v[46:49]
	v_mfma_f32_16x16x32_bf16 v[14:17], v[182:185], v[212:215], v[14:17]
	v_mfma_f32_16x16x32_bf16 v[42:45], v[166:169], v[220:223], v[42:45]
	v_mfma_f32_16x16x32_bf16 v[10:13], v[182:185], v[220:223], v[10:13]
	v_mfma_f32_16x16x32_bf16 v[38:41], v[166:169], v[228:231], v[38:41]
	v_mfma_f32_16x16x32_bf16 v[6:9], v[182:185], v[228:231], v[6:9]
	s_setprio 0
	s_add_i32 s83, s83, 2
	s_add_u32 s75, s75, 0x100
	s_addc_u32 s82, s82, 0
	s_add_u32 s76, s76, 0x100
	s_addc_u32 s77, s77, 0
	s_cmp_gt_u32 s83, 13
	s_cbranch_scc1 .Lk_p4_exit
	s_add_u32 s78, s76, 0xfffc0080
	s_addc_u32 s79, s77, -1
	s_add_i32 s84, 0, 0x10000
	s_cmp_eq_u32 s83, 12
	s_cselect_b32 s81, s56, s79
	s_cselect_b32 s80, s67, s78
	s_cselect_b32 s79, s65, s82
	s_cselect_b32 s78, s73, s75
	s_add_i32 s86, 0, 0x14000
	v_add_u32_e32 v146, s84, v177
	v_add_u32_e32 v174, s86, v177
	s_branch .Lk_p4_head
.Lk_p4_exit:
	s_barrier
	s_and_b64 vcc, exec, s[58:59]
	s_cbranch_vccz .LBB0_859
	s_barrier

; template <class Epi, class Sched, bool ALIGN_EPI = false, bool SP2 = false>
; __device__ __forceinline__ void gemm_phase(PG8_LAS unsigned char* lds, const Gemm g, const Sched& S, const Epi& E) {
;     ...
;         for (int t = 0; t < nt; t += 2) {
;             const bool last = (t == nt - 2);
;             const char* a1 = cA + (size_t)(t + 1) * kstep;
;             const char* a2 = last ? nA : cA + (size_t)(t + 2) * kstep; const char* b2 = last ? nB : cB + (size_t)(t + 2) * kstep;
;             const char* a3 = a2 + kstep; const char* b3 = b2 + kstep;
.LBB0_1035:
	s_add_u32 s24, s20, 0x100
	s_addc_u32 s25, s21, 0
	s_add_i32 s64, 0, 0x10000
	s_cmp_eq_u32 s63, 44
	s_cselect_b32 s59, s7, s25
	s_cselect_b32 s58, s6, s24
	v_add_u32_e32 v146, s64, v148
	s_cselect_b32 s27, s19, s62
	s_cselect_b32 s26, s18, s61
	s_add_i32 s65, 0, 0x14000
	s_branch .Lk_p5_body

; #define PG8_STAGE(bufoff, gbase, voff) do { _Pragma("unroll") for (int _i = 0; _i < 2; ++_i) \
;         __builtin_amdgcn_global_load_lds((const unsigned*)((const char*)(gbase) + (voff)[_i]), (PG8_LAS unsigned*)(lds + (bufoff) + ldsw + _i * 8192), 16, 0, 0); } while (0)
; #define PG8_LDA(dst, b, h) do { _Pragma("unroll") for (int m = 0; m < 4; ++m) _Pragma("unroll") for (int k = 0; k < 2; ++k) dst[m][k] = *(const PG8_LAS bf16x8*)(lds + PG8_SA(b, h) + aoff + m * 2048 + k * 1024); } while (0)
; #define PG8_LDB(dst, b, h) do { _Pragma("unroll") for (int n = 0; n < 2; ++n) _Pragma("unroll") for (int k = 0; k < 2; ++k) dst[n][k] = *(const PG8_LAS bf16x8*)(lds + PG8_SB(b, h) + boff + n * 2048 + k * 1024); } while (0)
; #define PG8_MMA(ai, bj, At, Bt) do { __builtin_amdgcn_s_setprio(1); _Pragma("unroll") for (int m = 0; m < 4; ++m) _Pragma("unroll") for (int n = 0; n < 2; ++n) _Pragma("unroll") for (int k = 0; k < 2; ++k) \
;         acc[ai][bj][m][n] = __builtin_amdgcn_mfma_f32_16x16x32_bf16(Bt[n][k], At[m][k], acc[ai][bj][m][n], 0, 0, 0); __builtin_amdgcn_s_setprio(0); } while (0)
; #define PG8_WAIT_V(n) asm volatile("s_waitcnt vmcnt(" #n ")" ::: "memory")
; #define PG8_WAIT_L(n) asm volatile("s_waitcnt lgkmcnt(" #n ")" ::: "memory")
; #define PG8_BAR __builtin_amdgcn_s_barrier()
; #define PG8_SCHED __builtin_amdgcn_sched_barrier(0)
; template <class Epi, class Sched, bool ALIGN_EPI = false, bool SP2 = false>
; __device__ __forceinline__ void gemm_phase(PG8_LAS unsigned char* lds, const Gemm g, const Sched& S, const Epi& E) {
;     ...
;             PG8_LDB(B0, 0, 0); PG8_LDB(B1, 0, 1); PG8_SCHED; PG8_LDA(At, 0, 0); PG8_STAGE(PG8_SA(1, 1), a1 + hstep, voffA);
;             PG8_WAIT_V(8); PG8_WAIT_L(0); PG8_BAR; PG8_MMA(0, 0, At, B0); PG8_MMA(0, 1, At, B1); PG8_BAR; PG8_SCHED;
;             PG8_LDA(At, 0, 1); PG8_STAGE(PG8_SB(0, 0), b2, voffB); PG8_STAGE(PG8_SB(0, 1), b2 + hstep, voffB); PG8_STAGE(PG8_SA(0, 0), a2, voffA);
;             PG8_WAIT_V(8); PG8_WAIT_L(0); PG8_BAR; PG8_MMA(1, 0, At, B0); PG8_MMA(1, 1, At, B1); PG8_BAR; PG8_SCHED;
.Lk_p5_body:
	ds_read_b128 v[142:145], v146
	ds_read_b128 v[152:155], v146 offset:1024
	ds_read_b128 v[156:159], v146 offset:2048
	ds_read_b128 v[160:163], v146 offset:3072
	v_add_u32_e32 v146, s65, v148
	ds_read_b128 v[164:167], v146
	ds_read_b128 v[168:171], v146 offset:1024
	ds_read_b128 v[172:175], v146 offset:2048
	ds_read_b128 v[180:183], v146 offset:3072
	v_lshl_add_u64 v[146:147], s[20:21], 0, v[140:141]
	s_add_i32 m0, s37, 0xc000
	ds_read_b128 v[184:187], v150
	ds_read_b128 v[200:203], v150 offset:1024
	ds_read_b128 v[204:207], v150 offset:2048
	ds_read_b128 v[208:211], v150 offset:3072
	ds_read_b128 v[212:215], v150 offset:4096
	ds_read_b128 v[216:219], v150 offset:5120
	ds_read_b128 v[220:223], v150 offset:6144
	ds_read_b128 v[224:227], v150 offset:7168
	global_load_lds_dwordx4 v[146:147], off
	v_lshl_add_u64 v[146:147], s[20:21], 0, v[138:139]
	s_add_i32 m0, s37, 0xe000
	s_nop 0
	global_load_lds_dwordx4 v[146:147], off
	s_waitcnt vmcnt(8)
	s_waitcnt lgkmcnt(0)
	s_barrier
	s_setprio 1
	s_waitcnt lgkmcnt(0)
	v_mfma_f32_16x16x32_bf16 v[130:133], v[142:145], v[184:187], v[130:133]
	v_mfma_f32_16x16x32_bf16 v[126:129], v[156:159], v[184:187], v[126:129]
	v_mfma_f32_16x16x32_bf16 v[118:121], v[142:145], v[204:207], v[118:121]
	v_mfma_f32_16x16x32_bf16 v[110:113], v[156:159], v[204:207], v[110:113]
	v_mfma_f32_16x16x32_bf16 v[102:105], v[142:145], v[212:215], v[102:105]
	v_mfma_f32_16x16x32_bf16 v[94:97], v[156:159], v[212:215], v[94:97]
	v_mfma_f32_16x16x32_bf16 v[86:89], v[142:145], v[220:223], v[86:89]
	v_mfma_f32_16x16x32_bf16 v[74:77], v[156:159], v[220:223], v[74:77]
	v_mfma_f32_16x16x32_bf16 v[130:133], v[152:155], v[200:203], v[130:133]
	v_mfma_f32_16x16x32_bf16 v[126:129], v[160:163], v[200:203], v[126:129]
	v_mfma_f32_16x16x32_bf16 v[118:121], v[152:155], v[208:211], v[118:121]
	v_mfma_f32_16x16x32_bf16 v[110:113], v[160:163], v[208:211], v[110:113]
	v_mfma_f32_16x16x32_bf16 v[102:105], v[152:155], v[216:219], v[102:105]
	v_mfma_f32_16x16x32_bf16 v[94:97], v[160:163], v[216:219], v[94:97]
	v_mfma_f32_16x16x32_bf16 v[86:89], v[152:155], v[224:227], v[86:89]
	v_mfma_f32_16x16x32_bf16 v[74:77], v[160:163], v[224:227], v[74:77]
	s_setprio 0
	s_setprio 1
	v_mfma_f32_16x16x32_bf16 v[122:125], v[164:167], v[184:187], v[122:125]
	v_mfma_f32_16x16x32_bf16 v[114:117], v[172:175], v[184:187], v[114:117]
	v_mfma_f32_16x16x32_bf16 v[106:109], v[164:167], v[204:207], v[106:109]
	v_mfma_f32_16x16x32_bf16 v[98:101], v[172:175], v[204:207], v[98:101]
	v_mfma_f32_16x16x32_bf16 v[90:93], v[164:167], v[212:215], v[90:93]
	v_mfma_f32_16x16x32_bf16 v[78:81], v[172:175], v[212:215], v[78:81]
	v_mfma_f32_16x16x32_bf16 v[70:73], v[164:167], v[220:223], v[70:73]
	v_mfma_f32_16x16x32_bf16 v[66:69], v[172:175], v[220:223], v[66:69]
	v_mfma_f32_16x16x32_bf16 v[122:125], v[168:171], v[200:203], v[122:125]
	v_mfma_f32_16x16x32_bf16 v[114:117], v[180:183], v[200:203], v[114:117]
	v_mfma_f32_16x16x32_bf16 v[106:109], v[168:171], v[208:211], v[106:109]
	v_mfma_f32_16x16x32_bf16 v[98:101], v[180:183], v[208:211], v[98:101]
	v_mfma_f32_16x16x32_bf16 v[90:93], v[168:171], v[216:219], v[90:93]
	v_mfma_f32_16x16x32_bf16 v[78:81], v[180:183], v[216:219], v[78:81]
	v_mfma_f32_16x16x32_bf16 v[70:73], v[168:171], v[224:227], v[70:73]
	v_mfma_f32_16x16x32_bf16 v[66:69], v[180:183], v[224:227], v[66:69]
	s_setprio 0
	s_barrier
	s_add_i32 s20, s64, s28
	v_lshl_add_u64 v[146:147], s[26:27], 0, v[136:137]
	s_mov_b32 m0, s20
	ds_read_b128 v[184:187], v150 offset:16384
	ds_read_b128 v[200:203], v150 offset:17408
	ds_read_b128 v[204:207], v150 offset:18432
	ds_read_b128 v[208:211], v150 offset:19456
	ds_read_b128 v[212:215], v150 offset:20480
	ds_read_b128 v[216:219], v150 offset:21504
	ds_read_b128 v[220:223], v150 offset:22528
	ds_read_b128 v[224:227], v150 offset:23552
	global_load_lds_dwordx4 v[146:147], off
	s_add_i32 m0, s20, 0x2000
	s_add_u32 s20, s26, 0xc0000
	v_lshl_add_u64 v[176:177], s[26:27], 0, v[134:135]
	s_addc_u32 s21, s27, 0
	s_add_i32 s64, s65, s28
	global_load_lds_dwordx4 v[176:177], off
	v_lshl_add_u64 v[228:229], s[20:21], 0, v[136:137]
	s_mov_b32 m0, s64
	v_lshl_add_u64 v[230:231], s[58:59], 0, v[134:135]
	global_load_lds_dwordx4 v[228:229], off
	v_lshl_add_u64 v[228:229], s[20:21], 0, v[134:135]
	s_add_i32 m0, s64, 0x2000
	s_nop 0
	global_load_lds_dwordx4 v[228:229], off
	v_lshl_add_u64 v[228:229], s[58:59], 0, v[136:137]
	s_mov_b32 m0, s37
	s_nop 0
	global_load_lds_dwordx4 v[228:229], off
	s_mov_b32 m0, s40
	s_nop 0
	global_load_lds_dwordx4 v[230:231], off
	s_waitcnt vmcnt(8)
	s_waitcnt lgkmcnt(0)
	s_barrier
; #define PG8_STAGE(bufoff, gbase, voff) do { _Pragma("unroll") for (int _i = 0; _i < 2; ++_i) \
;         __builtin_amdgcn_global_load_lds((const unsigned*)((const char*)(gbase) + (voff)[_i]), (PG8_LAS unsigned*)(lds + (bufoff) + ldsw + _i * 8192), 16, 0, 0); } while (0)
; #define PG8_LDA(dst, b, h) do { _Pragma("unroll") for (int m = 0; m < 4; ++m) _Pragma("unroll") for (int k = 0; k < 2; ++k) dst[m][k] = *(const PG8_LAS bf16x8*)(lds + PG8_SA(b, h) + aoff + m * 2048 + k * 1024); } while (0)
; #define PG8_LDB(dst, b, h) do { _Pragma("unroll") for (int n = 0; n < 2; ++n) _Pragma("unroll") for (int k = 0; k < 2; ++k) dst[n][k] = *(const PG8_LAS bf16x8*)(lds + PG8_SB(b, h) + boff + n * 2048 + k * 1024); } while (0)
; #define PG8_MMA(ai, bj, At, Bt) do { __builtin_amdgcn_s_setprio(1); _Pragma("unroll") for (int m = 0; m < 4; ++m) _Pragma("unroll") for (int n = 0; n < 2; ++n) _Pragma("unroll") for (int k = 0; k < 2; ++k) \
;         acc[ai][bj][m][n] = __builtin_amdgcn_mfma_f32_16x16x32_bf16(Bt[n][k], At[m][k], acc[ai][bj][m][n], 0, 0, 0); __builtin_amdgcn_s_setprio(0); } while (0)
; #define PG8_WAIT_V(n) asm volatile("s_waitcnt vmcnt(" #n ")" ::: "memory")
; #define PG8_WAIT_L(n) asm volatile("s_waitcnt lgkmcnt(" #n ")" ::: "memory")
; #define PG8_BAR __builtin_amdgcn_s_barrier()
; #define PG8_SCHED __builtin_amdgcn_sched_barrier(0)
; template <class Epi, class Sched, bool ALIGN_EPI = false, bool SP2 = false>
; __device__ __forceinline__ void gemm_phase(PG8_LAS unsigned char* lds, const Gemm g, const Sched& S, const Epi& E) {
;     ...
;             PG8_WAIT_V(8); PG8_WAIT_L(0); PG8_BAR; PG8_MMA(1, 0, At, B0); PG8_MMA(1, 1, At, B1); PG8_BAR; PG8_SCHED;
;             PG8_LDB(B0, 1, 0); PG8_LDB(B1, 1, 1); PG8_SCHED; PG8_LDA(At, 1, 0); PG8_STAGE(PG8_SA(0, 1), a2 + hstep, voffA);
;             PG8_WAIT_V(8); PG8_WAIT_L(0); PG8_BAR; PG8_MMA(0, 0, At, B0); PG8_MMA(0, 1, At, B1); PG8_BAR; PG8_SCHED;
	s_setprio 1
	s_waitcnt lgkmcnt(0)
	v_mfma_f32_16x16x32_bf16 v[62:65], v[142:145], v[184:187], v[62:65]
	v_mfma_f32_16x16x32_bf16 v[58:61], v[156:159], v[184:187], v[58:61]
	v_mfma_f32_16x16x32_bf16 v[50:53], v[142:145], v[204:207], v[50:53]
	v_mfma_f32_16x16x32_bf16 v[42:45], v[156:159], v[204:207], v[42:45]
	v_mfma_f32_16x16x32_bf16 v[34:37], v[142:145], v[212:215], v[34:37]
	v_mfma_f32_16x16x32_bf16 v[26:29], v[156:159], v[212:215], v[26:29]
	v_mfma_f32_16x16x32_bf16 v[18:21], v[142:145], v[220:223], v[18:21]
	v_mfma_f32_16x16x32_bf16 v[10:13], v[156:159], v[220:223], v[10:13]
	v_mfma_f32_16x16x32_bf16 v[62:65], v[152:155], v[200:203], v[62:65]
	v_mfma_f32_16x16x32_bf16 v[58:61], v[160:163], v[200:203], v[58:61]
	v_mfma_f32_16x16x32_bf16 v[50:53], v[152:155], v[208:211], v[50:53]
	v_mfma_f32_16x16x32_bf16 v[42:45], v[160:163], v[208:211], v[42:45]
	v_mfma_f32_16x16x32_bf16 v[34:37], v[152:155], v[216:219], v[34:37]
	v_mfma_f32_16x16x32_bf16 v[26:29], v[160:163], v[216:219], v[26:29]
	v_mfma_f32_16x16x32_bf16 v[18:21], v[152:155], v[224:227], v[18:21]
	v_mfma_f32_16x16x32_bf16 v[10:13], v[160:163], v[224:227], v[10:13]
	s_setprio 0
	s_setprio 1
	v_mfma_f32_16x16x32_bf16 v[54:57], v[164:167], v[184:187], v[54:57]
	v_mfma_f32_16x16x32_bf16 v[46:49], v[172:175], v[184:187], v[46:49]
	v_mfma_f32_16x16x32_bf16 v[38:41], v[164:167], v[204:207], v[38:41]
	v_mfma_f32_16x16x32_bf16 v[30:33], v[172:175], v[204:207], v[30:33]
	v_mfma_f32_16x16x32_bf16 v[22:25], v[164:167], v[212:215], v[22:25]
	v_mfma_f32_16x16x32_bf16 v[14:17], v[172:175], v[212:215], v[14:17]
	v_mfma_f32_16x16x32_bf16 v[6:9], v[164:167], v[220:223], v[6:9]
	v_mfma_f32_16x16x32_bf16 v[2:5], v[172:175], v[220:223], v[2:5]
	v_mfma_f32_16x16x32_bf16 v[54:57], v[168:171], v[200:203], v[54:57]
	v_mfma_f32_16x16x32_bf16 v[46:49], v[180:183], v[200:203], v[46:49]
	v_mfma_f32_16x16x32_bf16 v[38:41], v[168:171], v[208:211], v[38:41]
	v_mfma_f32_16x16x32_bf16 v[30:33], v[180:183], v[208:211], v[30:33]
	v_mfma_f32_16x16x32_bf16 v[22:25], v[168:171], v[216:219], v[22:25]
	v_mfma_f32_16x16x32_bf16 v[14:17], v[180:183], v[216:219], v[14:17]
	v_mfma_f32_16x16x32_bf16 v[6:9], v[168:171], v[224:227], v[6:9]
	v_mfma_f32_16x16x32_bf16 v[2:5], v[180:183], v[224:227], v[2:5]
	s_setprio 0
	s_barrier
	s_add_i32 s64, 0, 0x18000
	v_add_u32_e32 v151, s64, v148
	s_add_i32 s65, 0, 0x1c000
	ds_read_b128 v[142:145], v151
	ds_read_b128 v[152:155], v151 offset:1024
	ds_read_b128 v[156:159], v151 offset:2048
	ds_read_b128 v[160:163], v151 offset:3072
	v_add_u32_e32 v151, s65, v148
	ds_read_b128 v[164:167], v151
	ds_read_b128 v[168:171], v151 offset:1024
	ds_read_b128 v[172:175], v151 offset:2048
	ds_read_b128 v[180:183], v151 offset:3072
	s_add_u32 s20, s58, 0xc0000
	s_addc_u32 s21, s59, 0
	s_mov_b32 m0, s41
	v_lshl_add_u64 v[232:233], s[20:21], 0, v[136:137]
	ds_read_b128 v[184:187], v150 offset:32768
	ds_read_b128 v[200:203], v150 offset:33792
	ds_read_b128 v[204:207], v150 offset:34816
	ds_read_b128 v[208:211], v150 offset:35840
	ds_read_b128 v[212:215], v150 offset:36864
	ds_read_b128 v[216:219], v150 offset:37888
	ds_read_b128 v[220:223], v150 offset:38912
	ds_read_b128 v[224:227], v150 offset:39936
	global_load_lds_dwordx4 v[232:233], off
	v_lshl_add_u64 v[232:233], s[20:21], 0, v[134:135]
	s_mov_b32 m0, s42
	s_nop 0
	global_load_lds_dwordx4 v[232:233], off
	s_waitcnt vmcnt(8)
	s_waitcnt lgkmcnt(0)
	s_barrier
	s_setprio 1
	s_waitcnt lgkmcnt(0)
	v_mfma_f32_16x16x32_bf16 v[130:133], v[142:145], v[184:187], v[130:133]
	v_mfma_f32_16x16x32_bf16 v[126:129], v[156:159], v[184:187], v[126:129]
	v_mfma_f32_16x16x32_bf16 v[118:121], v[142:145], v[204:207], v[118:121]
	v_mfma_f32_16x16x32_bf16 v[110:113], v[156:159], v[204:207], v[110:113]
	v_mfma_f32_16x16x32_bf16 v[102:105], v[142:145], v[212:215], v[102:105]
	v_mfma_f32_16x16x32_bf16 v[94:97], v[156:159], v[212:215], v[94:97]
	v_mfma_f32_16x16x32_bf16 v[86:89], v[142:145], v[220:223], v[86:89]
	v_mfma_f32_16x16x32_bf16 v[74:77], v[156:159], v[220:223], v[74:77]
	v_mfma_f32_16x16x32_bf16 v[130:133], v[152:155], v[200:203], v[130:133]
	v_mfma_f32_16x16x32_bf16 v[126:129], v[160:163], v[200:203], v[126:129]
	v_mfma_f32_16x16x32_bf16 v[118:121], v[152:155], v[208:211], v[118:121]
	v_mfma_f32_16x16x32_bf16 v[110:113], v[160:163], v[208:211], v[110:113]
	v_mfma_f32_16x16x32_bf16 v[102:105], v[152:155], v[216:219], v[102:105]
	v_mfma_f32_16x16x32_bf16 v[94:97], v[160:163], v[216:219], v[94:97]
	v_mfma_f32_16x16x32_bf16 v[86:89], v[152:155], v[224:227], v[86:89]
	v_mfma_f32_16x16x32_bf16 v[74:77], v[160:163], v[224:227], v[74:77]
	s_setprio 0
	s_setprio 1
	v_mfma_f32_16x16x32_bf16 v[122:125], v[164:167], v[184:187], v[122:125]
	v_mfma_f32_16x16x32_bf16 v[114:117], v[172:175], v[184:187], v[114:117]
	v_mfma_f32_16x16x32_bf16 v[106:109], v[164:167], v[204:207], v[106:109]
	v_mfma_f32_16x16x32_bf16 v[98:101], v[172:175], v[204:207], v[98:101]
	v_mfma_f32_16x16x32_bf16 v[90:93], v[164:167], v[212:215], v[90:93]
	v_mfma_f32_16x16x32_bf16 v[78:81], v[172:175], v[212:215], v[78:81]
	v_mfma_f32_16x16x32_bf16 v[70:73], v[164:167], v[220:223], v[70:73]
	v_mfma_f32_16x16x32_bf16 v[66:69], v[172:175], v[220:223], v[66:69]
	v_mfma_f32_16x16x32_bf16 v[122:125], v[168:171], v[200:203], v[122:125]
	v_mfma_f32_16x16x32_bf16 v[114:117], v[180:183], v[200:203], v[114:117]
	v_mfma_f32_16x16x32_bf16 v[106:109], v[168:171], v[208:211], v[106:109]
	v_mfma_f32_16x16x32_bf16 v[98:101], v[180:183], v[208:211], v[98:101]
	v_mfma_f32_16x16x32_bf16 v[90:93], v[168:171], v[216:219], v[90:93]
	v_mfma_f32_16x16x32_bf16 v[78:81], v[180:183], v[216:219], v[78:81]
	v_mfma_f32_16x16x32_bf16 v[70:73], v[168:171], v[224:227], v[70:73]
	v_mfma_f32_16x16x32_bf16 v[66:69], v[180:183], v[224:227], v[66:69]
	s_setprio 0
	s_barrier
; #define PG8_STAGE(bufoff, gbase, voff) do { _Pragma("unroll") for (int _i = 0; _i < 2; ++_i) \
;         __builtin_amdgcn_global_load_lds((const unsigned*)((const char*)(gbase) + (voff)[_i]), (PG8_LAS unsigned*)(lds + (bufoff) + ldsw + _i * 8192), 16, 0, 0); } while (0)
; #define PG8_LDA(dst, b, h) do { _Pragma("unroll") for (int m = 0; m < 4; ++m) _Pragma("unroll") for (int k = 0; k < 2; ++k) dst[m][k] = *(const PG8_LAS bf16x8*)(lds + PG8_SA(b, h) + aoff + m * 2048 + k * 1024); } while (0)
; #define PG8_MMA(ai, bj, At, Bt) do { __builtin_amdgcn_s_setprio(1); _Pragma("unroll") for (int m = 0; m < 4; ++m) _Pragma("unroll") for (int n = 0; n < 2; ++n) _Pragma("unroll") for (int k = 0; k < 2; ++k) \
;         acc[ai][bj][m][n] = __builtin_amdgcn_mfma_f32_16x16x32_bf16(Bt[n][k], At[m][k], acc[ai][bj][m][n], 0, 0, 0); __builtin_amdgcn_s_setprio(0); } while (0)
; #define PG8_WAIT_V(n) asm volatile("s_waitcnt vmcnt(" #n ")" ::: "memory")
; #define PG8_WAIT_L(n) asm volatile("s_waitcnt lgkmcnt(" #n ")" ::: "memory")
; #define PG8_BAR __builtin_amdgcn_s_barrier()
; #define PG8_SCHED __builtin_amdgcn_sched_barrier(0)
; template <class Epi, class Sched, bool ALIGN_EPI = false, bool SP2 = false>
; __device__ __forceinline__ void gemm_phase(PG8_LAS unsigned char* lds, const Gemm g, const Sched& S, const Epi& E) {
;     ...
;         for (int t = 0; t < nt; t += 2) {
;             const bool last = (t == nt - 2);
;             const char* a1 = cA + (size_t)(t + 1) * kstep;
;             const char* a2 = last ? nA : cA + (size_t)(t + 2) * kstep; const char* b2 = last ? nB : cB + (size_t)(t + 2) * kstep;
;             const char* a3 = a2 + kstep; const char* b3 = b2 + kstep;
;     ...
;             PG8_LDA(At, 1, 1); PG8_STAGE(PG8_SB(1, 0), b3, voffB); PG8_STAGE(PG8_SB(1, 1), b3 + hstep, voffB); PG8_STAGE(PG8_SA(1, 0), a3, voffA);
;             PG8_WAIT_V(8); PG8_WAIT_L(0); PG8_BAR; PG8_MMA(1, 0, At, B0); PG8_MMA(1, 1, At, B1); PG8_BAR; PG8_SCHED;
	s_add_i32 s20, s64, s28
	v_lshl_add_u64 v[146:147], v[146:147], 0, s[38:39]
	s_mov_b32 m0, s20
	ds_read_b128 v[184:187], v150 offset:49152
	ds_read_b128 v[200:203], v150 offset:50176
	ds_read_b128 v[204:207], v150 offset:51200
	ds_read_b128 v[208:211], v150 offset:52224
	ds_read_b128 v[212:215], v150 offset:53248
	ds_read_b128 v[216:219], v150 offset:54272
	ds_read_b128 v[220:223], v150 offset:55296
	ds_read_b128 v[224:227], v150 offset:56320
	global_load_lds_dwordx4 v[146:147], off
	s_add_i32 m0, s20, 0x2000
	s_add_u32 s20, s26, 0xc0080
	v_lshl_add_u64 v[146:147], v[176:177], 0, s[38:39]
	s_addc_u32 s21, s27, 0
	s_add_i32 s26, s65, s28
	global_load_lds_dwordx4 v[146:147], off
	v_lshl_add_u64 v[146:147], s[20:21], 0, v[136:137]
	s_mov_b32 m0, s26
	s_nop 0
	global_load_lds_dwordx4 v[146:147], off
	v_lshl_add_u64 v[146:147], s[20:21], 0, v[134:135]
	s_add_i32 m0, s26, 0x2000
	s_nop 0
	global_load_lds_dwordx4 v[146:147], off
	v_lshl_add_u64 v[146:147], v[228:229], 0, s[38:39]
	s_mov_b32 m0, s49
	s_nop 0
	global_load_lds_dwordx4 v[146:147], off
	v_lshl_add_u64 v[146:147], v[230:231], 0, s[38:39]
	s_mov_b32 m0, s52
	s_nop 0
	global_load_lds_dwordx4 v[146:147], off
	s_waitcnt vmcnt(8)
	s_waitcnt lgkmcnt(0)
	s_barrier
	s_setprio 1
	s_waitcnt lgkmcnt(0)
	v_mfma_f32_16x16x32_bf16 v[62:65], v[142:145], v[184:187], v[62:65]
	v_mfma_f32_16x16x32_bf16 v[58:61], v[156:159], v[184:187], v[58:61]
	v_mfma_f32_16x16x32_bf16 v[50:53], v[142:145], v[204:207], v[50:53]
	v_mfma_f32_16x16x32_bf16 v[42:45], v[156:159], v[204:207], v[42:45]
	v_mfma_f32_16x16x32_bf16 v[34:37], v[142:145], v[212:215], v[34:37]
	v_mfma_f32_16x16x32_bf16 v[26:29], v[156:159], v[212:215], v[26:29]
	v_mfma_f32_16x16x32_bf16 v[18:21], v[142:145], v[220:223], v[18:21]
	v_mfma_f32_16x16x32_bf16 v[10:13], v[156:159], v[220:223], v[10:13]
	v_mfma_f32_16x16x32_bf16 v[62:65], v[152:155], v[200:203], v[62:65]
	v_mfma_f32_16x16x32_bf16 v[58:61], v[160:163], v[200:203], v[58:61]
	v_mfma_f32_16x16x32_bf16 v[50:53], v[152:155], v[208:211], v[50:53]
	v_mfma_f32_16x16x32_bf16 v[42:45], v[160:163], v[208:211], v[42:45]
	v_mfma_f32_16x16x32_bf16 v[34:37], v[152:155], v[216:219], v[34:37]
	v_mfma_f32_16x16x32_bf16 v[26:29], v[160:163], v[216:219], v[26:29]
	v_mfma_f32_16x16x32_bf16 v[18:21], v[152:155], v[224:227], v[18:21]
	v_mfma_f32_16x16x32_bf16 v[10:13], v[160:163], v[224:227], v[10:13]
	s_setprio 0
	s_setprio 1
	v_mfma_f32_16x16x32_bf16 v[54:57], v[164:167], v[184:187], v[54:57]
	v_mfma_f32_16x16x32_bf16 v[46:49], v[172:175], v[184:187], v[46:49]
	v_mfma_f32_16x16x32_bf16 v[38:41], v[164:167], v[204:207], v[38:41]
	v_mfma_f32_16x16x32_bf16 v[30:33], v[172:175], v[204:207], v[30:33]
	v_mfma_f32_16x16x32_bf16 v[22:25], v[164:167], v[212:215], v[22:25]
	v_mfma_f32_16x16x32_bf16 v[14:17], v[172:175], v[212:215], v[14:17]
	v_mfma_f32_16x16x32_bf16 v[6:9], v[164:167], v[220:223], v[6:9]
	v_mfma_f32_16x16x32_bf16 v[2:5], v[172:175], v[220:223], v[2:5]
	v_mfma_f32_16x16x32_bf16 v[54:57], v[168:171], v[200:203], v[54:57]
	v_mfma_f32_16x16x32_bf16 v[46:49], v[180:183], v[200:203], v[46:49]
	v_mfma_f32_16x16x32_bf16 v[38:41], v[168:171], v[208:211], v[38:41]
	v_mfma_f32_16x16x32_bf16 v[30:33], v[180:183], v[208:211], v[30:33]
	v_mfma_f32_16x16x32_bf16 v[22:25], v[168:171], v[216:219], v[22:25]
	v_mfma_f32_16x16x32_bf16 v[14:17], v[180:183], v[216:219], v[14:17]
	v_mfma_f32_16x16x32_bf16 v[6:9], v[168:171], v[224:227], v[6:9]
	v_mfma_f32_16x16x32_bf16 v[2:5], v[180:183], v[224:227], v[2:5]
	s_setprio 0
	s_add_i32 s63, s63, 2
	s_add_u32 s61, s61, 0x100
	s_addc_u32 s62, s62, 0
	s_cmp_gt_u32 s63, 45
	s_mov_b64 s[20:21], s[24:25]
	s_cbranch_scc1 .Lk_p5_exit
	s_add_u32 s24, s20, 0x100
	s_addc_u32 s25, s21, 0
	s_add_i32 s64, 0, 0x10000
	s_cmp_eq_u32 s63, 44
	s_cselect_b32 s59, s7, s25
	s_cselect_b32 s58, s6, s24
	v_add_u32_e32 v146, s64, v148
	s_cselect_b32 s27, s19, s62
	s_cselect_b32 s26, s18, s61
	s_add_i32 s65, 0, 0x14000
	s_branch .Lk_p5_head
